# GEMM loop back-edge rotation: next-iteration LDS address prep and stage rotation moved into the previous iteration MFMA gaps (loop head starts at the first MFMA)
# speedup vs baseline: 1.1002x; 1.0036x over previous
.LBB0_91:
	s_lshr_b32 s8, s10, 3
	s_and_b32 s8, s8, 0xffffff8
	s_and_b32 s9, s10, 7
	s_or_b32 s8, s8, s9
	s_and_b32 s9, s10, 56
	v_readlane_b32 s0, v252, 42
	s_or_b32 s11, s9, s0
	v_mov_b32_e32 v6, v171
	s_lshl_b32 s9, s11, 19
	v_lshlrev_b32_e32 v2, 3, v6
	s_add_u32 s12, s98, s9
	v_ashrrev_i32_e32 v3, 31, v2
	s_addc_u32 s13, s99, 0
	v_lshlrev_b64 v[4:5], 1, v[2:3]
	s_mov_b32 s9, s15
	v_lshl_add_u64 v[154:155], s[12:13], 0, v[4:5]
	s_mov_b64 s[74:75], s[12:13]
	s_lshl_b64 s[12:13], s[8:9], 18
	v_readlane_b32 s0, v252, 36
	v_readlane_b32 s1, v252, 37
	s_add_u32 s12, s0, s12
	s_addc_u32 s13, s1, s13
	v_lshrrev_b32_e32 v3, 2, v6
	v_and_b32_e32 v0, 24, v2
	v_lshl_add_u64 v[156:157], s[12:13], 0, v[4:5]
	s_mov_b64 s[76:77], s[12:13]
	v_mad_u64_u32 v[158:159], s[12:13], v3, 40, v[0:1]
	s_movk_i32 s0, 0x50
	v_and_b32_e32 v2, 0x30, v6
	v_xor_b32_e32 v140, v4, v2
	v_xor_b32_e32 v154, v154, v2
	v_xor_b32_e32 v156, v156, v2
	v_and_b32_e32 v130, 31, v6
	v_lshlrev_b32_e32 v130, 6, v130
	v_lshrrev_b32_e32 v131, 2, v6
	v_and_b32_e32 v131, 3, v131
	v_bfe_u32 v133, v6, 5, 1
	v_xor_b32_e32 v131, v131, v133
	v_lshl_or_b32 v130, v131, 4, v130
	v_lshrrev_b32_e32 v131, 7, v6
	v_lshl_or_b32 v132, v131, 13, v130
	v_bfe_u32 v131, v6, 6, 1
	v_lshl_or_b32 v133, v131, 12, v130
	v_or_b32_e32 v133, 0x4000, v133
	v_xor_b32_e32 v134, 32, v132
	v_xor_b32_e32 v135, 32, v133
	v_lshrrev_b32_e32 v131, 6, v6
	s_nop 1
	v_readfirstlane_b32 s72, v131
	s_nop 3
	s_lshl_b32 s72, s72, 10
	s_waitcnt lgkmcnt(0)
	s_barrier
	s_mov_b32 s14, 0
	s_lshl_b64 s[12:13], s[14:15], 14
	s_add_u32 s12, s12, s74
	s_addc_u32 s13, s13, s75
	s_add_u32 m0, s72, 0x0
	s_nop 0
	global_load_lds_dwordx4 v140, s[12:13]
	s_add_u32 m0, m0, 0x1000
	s_add_u32 s12, s12, 0x1000
	s_addc_u32 s13, s13, 0
	global_load_lds_dwordx4 v140, s[12:13]
	s_add_u32 m0, m0, 0x1000
	s_add_u32 s12, s12, 0x1000
	s_addc_u32 s13, s13, 0
	global_load_lds_dwordx4 v140, s[12:13]
	s_add_u32 m0, m0, 0x1000
	s_add_u32 s12, s12, 0x1000
	s_addc_u32 s13, s13, 0
	global_load_lds_dwordx4 v140, s[12:13]
	s_add_u32 m0, m0, 0x1000
	s_lshl_b64 s[12:13], s[14:15], 13
	s_add_u32 s12, s12, s76
	s_addc_u32 s13, s13, s77
	global_load_lds_dwordx4 v140, s[12:13]
	s_add_u32 m0, m0, 0x1000
	s_add_u32 s12, s12, 0x1000
	s_addc_u32 s13, s13, 0
	global_load_lds_dwordx4 v140, s[12:13]
	s_mov_b32 s14, 1
	s_lshl_b64 s[12:13], s[14:15], 14
	s_add_u32 s12, s12, s74
	s_addc_u32 s13, s13, s75
	s_add_u32 m0, s72, 0x6000
	s_nop 0
	global_load_lds_dwordx4 v140, s[12:13]
	s_add_u32 m0, m0, 0x1000
	s_add_u32 s12, s12, 0x1000
	s_addc_u32 s13, s13, 0
	global_load_lds_dwordx4 v140, s[12:13]
	s_add_u32 m0, m0, 0x1000
	s_add_u32 s12, s12, 0x1000
	s_addc_u32 s13, s13, 0
	global_load_lds_dwordx4 v140, s[12:13]
	s_add_u32 m0, m0, 0x1000
	s_add_u32 s12, s12, 0x1000
	s_addc_u32 s13, s13, 0
	global_load_lds_dwordx4 v140, s[12:13]
	s_add_u32 m0, m0, 0x1000
	s_lshl_b64 s[12:13], s[14:15], 13
	s_add_u32 s12, s12, s76
	s_addc_u32 s13, s13, s77
	global_load_lds_dwordx4 v140, s[12:13]
	s_add_u32 m0, m0, 0x1000
	s_add_u32 s12, s12, 0x1000
	s_addc_u32 s13, s13, 0
	global_load_lds_dwordx4 v140, s[12:13]
	s_mov_b32 s14, 2
	s_lshl_b64 s[12:13], s[14:15], 14
	s_add_u32 s12, s12, s74
	s_addc_u32 s13, s13, s75
	s_add_u32 m0, s72, 0xc000
	s_nop 0
	global_load_lds_dwordx4 v140, s[12:13]
	s_add_u32 m0, m0, 0x1000
	s_add_u32 s12, s12, 0x1000
	s_addc_u32 s13, s13, 0
	global_load_lds_dwordx4 v140, s[12:13]
	s_add_u32 m0, m0, 0x1000
	s_add_u32 s12, s12, 0x1000
	s_addc_u32 s13, s13, 0
	global_load_lds_dwordx4 v140, s[12:13]
	s_add_u32 m0, m0, 0x1000
	s_add_u32 s12, s12, 0x1000
	s_addc_u32 s13, s13, 0
	global_load_lds_dwordx4 v140, s[12:13]
	s_add_u32 m0, m0, 0x1000
	s_lshl_b64 s[12:13], s[14:15], 13
	s_add_u32 s12, s12, s76
	s_addc_u32 s13, s13, s77
	global_load_lds_dwordx4 v140, s[12:13]
	s_add_u32 m0, m0, 0x1000
	s_add_u32 s12, s12, 0x1000
	s_addc_u32 s13, s13, 0
	global_load_lds_dwordx4 v140, s[12:13]
	v_and_b32_e32 v2, 0xfffff9f, v6
	v_mul_lo_u32 v160, v2, s0
	v_or_b32_e32 v2, 0x60, v6
	v_lshrrev_b32_e32 v0, 1, v6
	v_and_b32_e32 v3, 0x5f, v6
	v_mul_lo_u32 v161, v2, s0
	v_mov_b32_e32 v2, 0
	s_mov_b32 s9, 0
	v_and_b32_e32 v0, 16, v0
	v_mul_u32_u24_e32 v159, 0x50, v3
	v_mov_b32_e32 v3, v2
	v_mov_b32_e32 v4, v2
	v_mov_b32_e32 v5, v2
	v_mov_b32_e32 v6, v2
	v_mov_b32_e32 v7, v2
	v_mov_b32_e32 v8, v2
	v_mov_b32_e32 v9, v2
	v_mov_b32_e32 v10, v2
	v_mov_b32_e32 v11, v2
	v_mov_b32_e32 v12, v2
	v_mov_b32_e32 v13, v2
	v_mov_b32_e32 v14, v2
	v_mov_b32_e32 v15, v2
	v_mov_b32_e32 v16, v2
	v_mov_b32_e32 v17, v2
	v_mov_b32_e32 v18, v2
	v_mov_b32_e32 v19, v2
	v_mov_b32_e32 v20, v2
	v_mov_b32_e32 v21, v2
	v_mov_b32_e32 v22, v2
	v_mov_b32_e32 v23, v2
	v_mov_b32_e32 v24, v2
	v_mov_b32_e32 v25, v2
	v_mov_b32_e32 v26, v2
	v_mov_b32_e32 v27, v2
	v_mov_b32_e32 v28, v2
	v_mov_b32_e32 v29, v2
	v_mov_b32_e32 v30, v2
	v_mov_b32_e32 v31, v2
	v_mov_b32_e32 v32, v2
	v_mov_b32_e32 v33, v2
	v_mov_b32_e32 v34, v2
	v_mov_b32_e32 v35, v2
	v_mov_b32_e32 v36, v2
	v_mov_b32_e32 v37, v2
	v_mov_b32_e32 v38, v2
	v_mov_b32_e32 v39, v2
	v_mov_b32_e32 v40, v2
	v_mov_b32_e32 v41, v2
	v_mov_b32_e32 v42, v2
	v_mov_b32_e32 v43, v2
	v_mov_b32_e32 v44, v2
	v_mov_b32_e32 v45, v2
	v_mov_b32_e32 v46, v2
	v_mov_b32_e32 v47, v2
	v_mov_b32_e32 v48, v2
	v_mov_b32_e32 v49, v2
	v_mov_b32_e32 v50, v2
	v_mov_b32_e32 v51, v2
	v_mov_b32_e32 v52, v2
	v_mov_b32_e32 v53, v2
	v_mov_b32_e32 v54, v2
	v_mov_b32_e32 v55, v2
	v_mov_b32_e32 v56, v2
	v_mov_b32_e32 v57, v2
	v_mov_b32_e32 v58, v2
	v_mov_b32_e32 v59, v2
	v_mov_b32_e32 v60, v2
	v_mov_b32_e32 v61, v2
	v_mov_b32_e32 v62, v2
	v_mov_b32_e32 v63, v2
	v_mov_b32_e32 v64, v2
	v_mov_b32_e32 v65, v2
	v_mov_b32_e32 v66, v2
	v_mov_b32_e32 v67, v2
	v_mov_b32_e32 v68, v2
	v_mov_b32_e32 v69, v2
	v_mov_b32_e32 v70, v2
	v_mov_b32_e32 v71, v2
	v_mov_b32_e32 v72, v2
	v_mov_b32_e32 v73, v2
	v_mov_b32_e32 v74, v2
	v_mov_b32_e32 v75, v2
	v_mov_b32_e32 v76, v2
	v_mov_b32_e32 v77, v2
	v_mov_b32_e32 v78, v2
	v_mov_b32_e32 v79, v2
	v_mov_b32_e32 v80, v2
	v_mov_b32_e32 v81, v2
	s_waitcnt vmcnt(17)
	v_mov_b32_e32 v82, v2
	v_mov_b32_e32 v83, v2
	v_mov_b32_e32 v84, v2
	v_mov_b32_e32 v85, v2
	s_waitcnt vmcnt(16)
	v_mov_b32_e32 v86, v2
	v_mov_b32_e32 v87, v2
	v_mov_b32_e32 v88, v2
	v_mov_b32_e32 v89, v2
	s_waitcnt vmcnt(15)
	v_mov_b32_e32 v90, v2
	v_mov_b32_e32 v91, v2
	v_mov_b32_e32 v92, v2
	v_mov_b32_e32 v93, v2
	s_waitcnt vmcnt(14)
	v_mov_b32_e32 v94, v2
	v_mov_b32_e32 v95, v2
	v_mov_b32_e32 v96, v2
	v_mov_b32_e32 v97, v2
	v_mov_b32_e32 v98, v2
	v_mov_b32_e32 v99, v2
	v_mov_b32_e32 v100, v2
	v_mov_b32_e32 v101, v2
	v_mov_b32_e32 v102, v2
	v_mov_b32_e32 v103, v2
	v_mov_b32_e32 v104, v2
	v_mov_b32_e32 v105, v2
	v_mov_b32_e32 v106, v2
	v_mov_b32_e32 v107, v2
	v_mov_b32_e32 v108, v2
	v_mov_b32_e32 v109, v2
	v_mov_b32_e32 v110, v2
	v_mov_b32_e32 v111, v2
	v_mov_b32_e32 v112, v2
	v_mov_b32_e32 v113, v2
	v_mov_b32_e32 v114, v2
	v_mov_b32_e32 v115, v2
	v_mov_b32_e32 v116, v2
	v_mov_b32_e32 v117, v2
	v_mov_b32_e32 v118, v2
	v_mov_b32_e32 v119, v2
	v_mov_b32_e32 v120, v2
	v_mov_b32_e32 v121, v2
	v_mov_b32_e32 v122, v2
	v_mov_b32_e32 v123, v2
	v_mov_b32_e32 v124, v2
	v_mov_b32_e32 v125, v2
	v_mov_b32_e32 v126, v2
	v_mov_b32_e32 v127, v2
	v_mov_b32_e32 v128, v2
	v_mov_b32_e32 v129, v2
	s_mov_b32 s9, 0
	s_mov_b32 s34, 0
	v_mov_b32_e32 v138, v132
	v_mov_b32_e32 v139, v133
	s_waitcnt vmcnt(12)
	s_barrier
	ds_read_b128 v[162:165], v138 offset:0
	ds_read_b128 v[228:231], v139 offset:0
	ds_read_b128 v[236:239], v139 offset:2048
	ds_read_b128 v[204:207], v138 offset:2048
	ds_read_b128 v[212:215], v138 offset:4096
	ds_read_b128 v[220:223], v138 offset:6144
	s_movk_i32 s73, 0x6000
	v_mov_b32_e32 v136, v134
	v_mov_b32_e32 v137, v135
	v_add_u32_e32 v138, s73, v132
	v_add_u32_e32 v139, s73, v133
.Lg92_loop:
	s_waitcnt lgkmcnt(0)
	v_mfma_f32_32x32x16_bf16 v[114:129], v[162:165], v[228:231], v[114:129]
	ds_read_b128 v[166:169], v136 offset:0
	ds_read_b128 v[232:235], v137 offset:0
	s_add_i32 s9, s9, 1
	s_add_i32 s14, s9, 2
	s_lshl_b64 s[12:13], s[14:15], 14
	s_add_u32 s12, s12, s74
	s_addc_u32 s13, s13, s75
	v_mfma_f32_32x32x16_bf16 v[98:113], v[162:165], v[236:239], v[98:113]
	ds_read_b128 v[240:243], v137 offset:2048
	ds_read_b128 v[208:211], v136 offset:2048
	v_mfma_f32_32x32x16_bf16 v[82:97], v[204:207], v[228:231], v[82:97]
	ds_read_b128 v[216:219], v136 offset:4096
	ds_read_b128 v[224:227], v136 offset:6144
	v_mfma_f32_32x32x16_bf16 v[66:81], v[204:207], v[236:239], v[66:81]
	v_mfma_f32_32x32x16_bf16 v[50:65], v[212:215], v[228:231], v[50:65]
	v_mfma_f32_32x32x16_bf16 v[34:49], v[212:215], v[236:239], v[34:49]
	v_mfma_f32_32x32x16_bf16 v[18:33], v[220:223], v[228:231], v[18:33]
	v_mfma_f32_32x32x16_bf16 v[2:17], v[220:223], v[236:239], v[2:17]
	s_waitcnt vmcnt(6) lgkmcnt(0)
	s_barrier
	s_add_u32 m0, s34, s72
	s_mov_b32 s34, s73
	s_add_u32 s73, s34, 0x6000
	s_cmp_lt_u32 s73, 0x12000
	s_cselect_b32 s73, s73, 0
	v_mfma_f32_32x32x16_bf16 v[114:129], v[166:169], v[232:235], v[114:129]
	ds_read_b128 v[162:165], v138 offset:0
	ds_read_b128 v[228:231], v139 offset:0
	v_mfma_f32_32x32x16_bf16 v[98:113], v[166:169], v[240:243], v[98:113]
	ds_read_b128 v[236:239], v139 offset:2048
	ds_read_b128 v[204:207], v138 offset:2048
	v_add_u32_e32 v136, s34, v134
	v_add_u32_e32 v137, s34, v135
	v_mfma_f32_32x32x16_bf16 v[82:97], v[208:211], v[232:235], v[82:97]
	ds_read_b128 v[212:215], v138 offset:4096
	ds_read_b128 v[220:223], v138 offset:6144
	v_mfma_f32_32x32x16_bf16 v[66:81], v[208:211], v[240:243], v[66:81]
	global_load_lds_dwordx4 v140, s[12:13]
	s_add_u32 m0, m0, 0x1000
	s_add_u32 s12, s12, 0x1000
	s_addc_u32 s13, s13, 0
	v_add_u32_e32 v138, s73, v132
	v_add_u32_e32 v139, s73, v133
	v_mfma_f32_32x32x16_bf16 v[50:65], v[216:219], v[232:235], v[50:65]
	global_load_lds_dwordx4 v140, s[12:13]
	s_add_u32 m0, m0, 0x1000
	s_add_u32 s12, s12, 0x1000
	s_addc_u32 s13, s13, 0
	v_mfma_f32_32x32x16_bf16 v[34:49], v[216:219], v[240:243], v[34:49]
	global_load_lds_dwordx4 v140, s[12:13]
	s_add_u32 m0, m0, 0x1000
	s_add_u32 s12, s12, 0x1000
	s_addc_u32 s13, s13, 0
	v_mfma_f32_32x32x16_bf16 v[18:33], v[224:227], v[232:235], v[18:33]
	global_load_lds_dwordx4 v140, s[12:13]
	s_add_u32 m0, m0, 0x1000
	s_lshl_b64 s[12:13], s[14:15], 13
	s_add_u32 s12, s12, s76
	s_addc_u32 s13, s13, s77
	v_mfma_f32_32x32x16_bf16 v[2:17], v[224:227], v[240:243], v[2:17]
	global_load_lds_dwordx4 v140, s[12:13]
	s_add_u32 m0, m0, 0x1000
	s_add_u32 s12, s12, 0x1000
	s_addc_u32 s13, s13, 0
	s_nop 0
	global_load_lds_dwordx4 v140, s[12:13]
	s_cmp_lg_u32 s9, 29
	s_cbranch_scc1 .Lg92_loop
	s_waitcnt lgkmcnt(0)
	v_mfma_f32_32x32x16_bf16 v[114:129], v[162:165], v[228:231], v[114:129]
	ds_read_b128 v[166:169], v136 offset:0
	ds_read_b128 v[232:235], v137 offset:0
	s_add_i32 s9, s9, 1
	v_mfma_f32_32x32x16_bf16 v[98:113], v[162:165], v[236:239], v[98:113]
	ds_read_b128 v[240:243], v137 offset:2048
	ds_read_b128 v[208:211], v136 offset:2048
	v_mfma_f32_32x32x16_bf16 v[82:97], v[204:207], v[228:231], v[82:97]
	ds_read_b128 v[216:219], v136 offset:4096
	ds_read_b128 v[224:227], v136 offset:6144
	v_mfma_f32_32x32x16_bf16 v[66:81], v[204:207], v[236:239], v[66:81]
	v_mfma_f32_32x32x16_bf16 v[50:65], v[212:215], v[228:231], v[50:65]
	v_mfma_f32_32x32x16_bf16 v[34:49], v[212:215], v[236:239], v[34:49]
	v_mfma_f32_32x32x16_bf16 v[18:33], v[220:223], v[228:231], v[18:33]
	v_mfma_f32_32x32x16_bf16 v[2:17], v[220:223], v[236:239], v[2:17]
	s_waitcnt vmcnt(6) lgkmcnt(0)
	s_barrier
	s_mov_b32 s34, s73
	s_add_u32 s73, s34, 0x6000
	s_cmp_lt_u32 s73, 0x12000
	s_cselect_b32 s73, s73, 0
	v_mfma_f32_32x32x16_bf16 v[114:129], v[166:169], v[232:235], v[114:129]
	ds_read_b128 v[162:165], v138 offset:0
	ds_read_b128 v[228:231], v139 offset:0
	v_mfma_f32_32x32x16_bf16 v[98:113], v[166:169], v[240:243], v[98:113]
	ds_read_b128 v[236:239], v139 offset:2048
	ds_read_b128 v[204:207], v138 offset:2048
	v_add_u32_e32 v136, s34, v134
	v_add_u32_e32 v137, s34, v135
	v_mfma_f32_32x32x16_bf16 v[82:97], v[208:211], v[232:235], v[82:97]
	ds_read_b128 v[212:215], v138 offset:4096
	ds_read_b128 v[220:223], v138 offset:6144
	v_mfma_f32_32x32x16_bf16 v[66:81], v[208:211], v[240:243], v[66:81]
	v_add_u32_e32 v138, s73, v132
	v_add_u32_e32 v139, s73, v133
	v_mfma_f32_32x32x16_bf16 v[50:65], v[216:219], v[232:235], v[50:65]
	v_mfma_f32_32x32x16_bf16 v[34:49], v[216:219], v[240:243], v[34:49]
	v_mfma_f32_32x32x16_bf16 v[18:33], v[224:227], v[232:235], v[18:33]
	v_mfma_f32_32x32x16_bf16 v[2:17], v[224:227], v[240:243], v[2:17]
	s_waitcnt lgkmcnt(0)
	v_mfma_f32_32x32x16_bf16 v[114:129], v[162:165], v[228:231], v[114:129]
	ds_read_b128 v[166:169], v136 offset:0
	ds_read_b128 v[232:235], v137 offset:0
	s_add_i32 s9, s9, 1
	v_mfma_f32_32x32x16_bf16 v[98:113], v[162:165], v[236:239], v[98:113]
	ds_read_b128 v[240:243], v137 offset:2048
	ds_read_b128 v[208:211], v136 offset:2048
	v_mfma_f32_32x32x16_bf16 v[82:97], v[204:207], v[228:231], v[82:97]
	ds_read_b128 v[216:219], v136 offset:4096
	ds_read_b128 v[224:227], v136 offset:6144
	v_mfma_f32_32x32x16_bf16 v[66:81], v[204:207], v[236:239], v[66:81]
	v_mfma_f32_32x32x16_bf16 v[50:65], v[212:215], v[228:231], v[50:65]
	v_mfma_f32_32x32x16_bf16 v[34:49], v[212:215], v[236:239], v[34:49]
	v_mfma_f32_32x32x16_bf16 v[18:33], v[220:223], v[228:231], v[18:33]
	v_mfma_f32_32x32x16_bf16 v[2:17], v[220:223], v[236:239], v[2:17]
	s_waitcnt vmcnt(0) lgkmcnt(0)
	s_barrier
	s_mov_b32 s34, s73
	s_add_u32 s73, s34, 0x6000
	s_cmp_lt_u32 s73, 0x12000
	s_cselect_b32 s73, s73, 0
	v_mfma_f32_32x32x16_bf16 v[114:129], v[166:169], v[232:235], v[114:129]
	ds_read_b128 v[162:165], v138 offset:0
	ds_read_b128 v[228:231], v139 offset:0
	v_mfma_f32_32x32x16_bf16 v[98:113], v[166:169], v[240:243], v[98:113]
	ds_read_b128 v[236:239], v139 offset:2048
	ds_read_b128 v[204:207], v138 offset:2048
	v_add_u32_e32 v136, s34, v134
	v_add_u32_e32 v137, s34, v135
	v_mfma_f32_32x32x16_bf16 v[82:97], v[208:211], v[232:235], v[82:97]
	ds_read_b128 v[212:215], v138 offset:4096
	ds_read_b128 v[220:223], v138 offset:6144
	v_mfma_f32_32x32x16_bf16 v[66:81], v[208:211], v[240:243], v[66:81]
	v_add_u32_e32 v138, s73, v132
	v_add_u32_e32 v139, s73, v133
	v_mfma_f32_32x32x16_bf16 v[50:65], v[216:219], v[232:235], v[50:65]
	v_mfma_f32_32x32x16_bf16 v[34:49], v[216:219], v[240:243], v[34:49]
	v_mfma_f32_32x32x16_bf16 v[18:33], v[224:227], v[232:235], v[18:33]
	v_mfma_f32_32x32x16_bf16 v[2:17], v[224:227], v[240:243], v[2:17]
	s_waitcnt lgkmcnt(0)
	v_mfma_f32_32x32x16_bf16 v[114:129], v[162:165], v[228:231], v[114:129]
	ds_read_b128 v[166:169], v136 offset:0
	ds_read_b128 v[232:235], v137 offset:0
	s_add_i32 s9, s9, 1
	v_mfma_f32_32x32x16_bf16 v[98:113], v[162:165], v[236:239], v[98:113]
	ds_read_b128 v[240:243], v137 offset:2048
	ds_read_b128 v[208:211], v136 offset:2048
	v_mfma_f32_32x32x16_bf16 v[82:97], v[204:207], v[228:231], v[82:97]
	ds_read_b128 v[216:219], v136 offset:4096
	ds_read_b128 v[224:227], v136 offset:6144
	v_mfma_f32_32x32x16_bf16 v[66:81], v[204:207], v[236:239], v[66:81]
	v_mfma_f32_32x32x16_bf16 v[50:65], v[212:215], v[228:231], v[50:65]
	v_mfma_f32_32x32x16_bf16 v[34:49], v[212:215], v[236:239], v[34:49]
	v_mfma_f32_32x32x16_bf16 v[18:33], v[220:223], v[228:231], v[18:33]
	v_mfma_f32_32x32x16_bf16 v[2:17], v[220:223], v[236:239], v[2:17]
	s_waitcnt lgkmcnt(0)
	v_mfma_f32_32x32x16_bf16 v[114:129], v[166:169], v[232:235], v[114:129]
	v_mfma_f32_32x32x16_bf16 v[98:113], v[166:169], v[240:243], v[98:113]
	v_mfma_f32_32x32x16_bf16 v[82:97], v[208:211], v[232:235], v[82:97]
	v_mfma_f32_32x32x16_bf16 v[66:81], v[208:211], v[240:243], v[66:81]
	v_mfma_f32_32x32x16_bf16 v[50:65], v[216:219], v[232:235], v[50:65]
	v_mfma_f32_32x32x16_bf16 v[34:49], v[216:219], v[240:243], v[34:49]
	v_mfma_f32_32x32x16_bf16 v[18:33], v[224:227], v[232:235], v[18:33]
	v_mfma_f32_32x32x16_bf16 v[2:17], v[224:227], v[240:243], v[2:17]
	s_mov_b32 s14, 31
	s_lshl_b64 s[12:13], s[14:15], 13
	s_movk_i32 s34, 0x7800
	s_movk_i32 s72, 0x6000
	s_mov_b32 s73, 0xc000
	s_movk_i32 s74, 0x104
	s_mov_b32 s75, 0x42ce8ed0
	s_mov_b32 s76, 0xbfb8aa3b
	s_mov_b32 s77, 0x1d730000
	v_mov_b32_e32 v0, v171
	s_barrier
	s_waitcnt vmcnt(4)
	v_lshrrev_b32_e32 v130, 1, v0
	v_and_b32_e32 v130, 0xfffffc0, v130
	v_lshrrev_b32_e32 v131, 3, v0
	v_and_or_b32 v130, v131, 4, v130
	v_and_b32_e32 v0, 0x5f, v0
	v_mul_lo_u32 v130, v130, s53
	v_lshl_add_u32 v0, v0, 2, v130
	s_barrier
	ds_write2_b32 v0, v114, v98 offset1:32
	ds_write2_b32 v0, v115, v99 offset0:132 offset1:164
	v_add_u32_e32 v98, 0x400, v0
	ds_write2_b32 v98, v116, v100 offset0:8 offset1:40
	ds_write2_b32 v98, v117, v101 offset0:140 offset1:172
	v_add_u32_e32 v98, 0x1000, v0
	ds_write2_b32 v98, v118, v102 offset0:32 offset1:64
	ds_write2_b32 v98, v119, v103 offset0:164 offset1:196
	v_add_u32_e32 v98, 0x1400, v0
	ds_write2_b32 v98, v120, v104 offset0:40 offset1:72
	ds_write2_b32 v98, v121, v105 offset0:172 offset1:204
	v_add_u32_e32 v98, 0x2000, v0
	ds_write2_b32 v98, v122, v106 offset0:64 offset1:96
	ds_write2_b32 v98, v123, v107 offset0:196 offset1:228
	v_add_u32_e32 v98, 0x2400, v0
	ds_write2_b32 v98, v124, v108 offset0:72 offset1:104
	ds_write2_b32 v98, v125, v109 offset0:204 offset1:236
	v_add_u32_e32 v98, 0x3000, v0
	ds_write2_b32 v98, v126, v110 offset0:96 offset1:128
	v_add_u32_e32 v98, 0x3200, v0
	ds_write2_b32 v98, v127, v111 offset0:100 offset1:132
	v_add_u32_e32 v98, 0x3400, v0
	ds_write2_b32 v98, v128, v112 offset0:104 offset1:136
	v_add_u32_e32 v98, 0x3600, v0
	ds_write2_b32 v98, v129, v113 offset0:108 offset1:140
	v_add_u32_e32 v98, 0x4000, v0
	ds_write2_b32 v98, v82, v66 offset0:128 offset1:160
	v_add_u32_e32 v66, 0x4400, v0
	ds_write2_b32 v66, v83, v67 offset0:4 offset1:36
	ds_write2_b32 v66, v84, v68 offset0:136 offset1:168
	v_add_u32_e32 v66, 0x4800, v0
	ds_write2_b32 v66, v85, v69 offset0:12 offset1:44
	v_add_u32_e32 v66, 0x5000, v0
	ds_write2_b32 v66, v86, v70 offset0:160 offset1:192
	v_add_u32_e32 v66, 0x5400, v0
	ds_write2_b32 v66, v87, v71 offset0:36 offset1:68
	ds_write2_b32 v66, v88, v72 offset0:168 offset1:200
	v_add_u32_e32 v66, 0x5800, v0
	ds_write2_b32 v66, v89, v73 offset0:44 offset1:76
	v_add_u32_e32 v66, 0x6000, v0
	ds_write2_b32 v66, v90, v74 offset0:192 offset1:224
	v_add_u32_e32 v66, 0x6400, v0
	ds_write2_b32 v66, v91, v75 offset0:68 offset1:100
	ds_write2_b32 v66, v92, v76 offset0:200 offset1:232
	v_add_u32_e32 v66, 0x6800, v0
	ds_write2_b32 v66, v93, v77 offset0:76 offset1:108
	v_add_u32_e32 v66, 0x7200, v0
	ds_write2_b32 v66, v94, v78 offset0:96 offset1:128
	v_add_u32_e32 v66, 0x7400, v0
	ds_write2_b32 v66, v95, v79 offset0:100 offset1:132
	v_add_u32_e32 v66, 0x7600, v0
	v_add_u32_e32 v0, 0x7800, v0
	v_mov_b32_e32 v74, v171
	ds_write2_b32 v66, v96, v80 offset0:104 offset1:136
	ds_write2_b32 v0, v97, v81 offset0:108 offset1:140
	s_waitcnt lgkmcnt(0)
	s_barrier
	s_lshl_b32 s8, s8, 7
	v_lshlrev_b32_e32 v75, 3, v74
	v_and_b32_e32 v0, 0x78, v75
	v_or_b32_e32 v0, s8, v0
	v_lshl_add_u64 v[70:71], v[0:1], 2, s[6:7]
	global_load_dwordx4 v[66:69], v[70:71], off
	s_nop 0
	global_load_dwordx4 v[70:73], v[70:71], off offset:16
	v_ashrrev_i32_e32 v76, 4, v74
	v_lshrrev_b32_e32 v77, 5, v0
	v_and_b32_e32 v0, 24, v75
	v_mul_lo_u32 v75, v76, s53
	v_and_b32_e32 v74, 15, v74
	v_readlane_b32 s0, v252, 46
	s_lshl_b32 s9, s11, 8
	v_lshl_add_u32 v78, v74, 5, v75
	v_lshlrev_b32_e32 v79, 1, v76
	s_mov_b32 s11, 0
	v_lshlrev_b32_e32 v74, 1, v0
	v_readlane_b32 s1, v252, 47
	s_waitcnt vmcnt(0)

.LBB0_356:
	s_lshr_b32 s6, s12, 3
	s_and_b32 s8, s12, 56
	v_readlane_b32 s0, v252, 42
	s_and_b32 s6, s6, 0xffffff8
	s_and_b32 s7, s12, 7
	s_or_b32 s9, s8, s0
	v_mov_b32_e32 v6, v171
	s_or_b32 s6, s6, s7
	s_lshl_b32 s7, s9, 19
	v_lshlrev_b32_e32 v2, 3, v6
	s_add_u32 s10, s98, s7
	v_ashrrev_i32_e32 v3, 31, v2
	s_addc_u32 s11, s99, 0
	v_lshlrev_b64 v[4:5], 1, v[2:3]
	s_mov_b32 s7, s15
	v_lshl_add_u64 v[154:155], s[10:11], 0, v[4:5]
	s_mov_b64 s[74:75], s[10:11]
	s_lshl_b64 s[10:11], s[6:7], 18
	v_readlane_b32 s0, v252, 38
	v_readlane_b32 s1, v252, 39
	s_add_u32 s10, s0, s10
	s_addc_u32 s11, s1, s11
	v_lshrrev_b32_e32 v3, 2, v6
	v_and_b32_e32 v0, 24, v2
	v_lshl_add_u64 v[156:157], s[10:11], 0, v[4:5]
	s_mov_b64 s[76:77], s[10:11]
	v_mad_u64_u32 v[158:159], s[10:11], v3, 40, v[0:1]
	s_movk_i32 s0, 0x50
	v_and_b32_e32 v2, 0x30, v6
	v_xor_b32_e32 v140, v4, v2
	v_xor_b32_e32 v154, v154, v2
	v_xor_b32_e32 v156, v156, v2
	v_and_b32_e32 v130, 31, v6
	v_lshlrev_b32_e32 v130, 6, v130
	v_lshrrev_b32_e32 v131, 2, v6
	v_and_b32_e32 v131, 3, v131
	v_bfe_u32 v133, v6, 5, 1
	v_xor_b32_e32 v131, v131, v133
	v_lshl_or_b32 v130, v131, 4, v130
	v_lshrrev_b32_e32 v131, 7, v6
	v_lshl_or_b32 v132, v131, 13, v130
	v_bfe_u32 v131, v6, 6, 1
	v_lshl_or_b32 v133, v131, 12, v130
	v_or_b32_e32 v133, 0x4000, v133
	v_xor_b32_e32 v134, 32, v132
	v_xor_b32_e32 v135, 32, v133
	v_lshrrev_b32_e32 v131, 6, v6
	s_nop 1
	v_readfirstlane_b32 s72, v131
	s_nop 3
	s_lshl_b32 s72, s72, 10
	s_waitcnt lgkmcnt(0)
	s_barrier
	s_mov_b32 s14, 0
	s_lshl_b64 s[10:11], s[14:15], 14
	s_add_u32 s10, s10, s74
	s_addc_u32 s11, s11, s75
	s_add_u32 m0, s72, 0x0
	s_nop 0
	global_load_lds_dwordx4 v140, s[10:11]
	s_add_u32 m0, m0, 0x1000
	s_add_u32 s10, s10, 0x1000
	s_addc_u32 s11, s11, 0
	global_load_lds_dwordx4 v140, s[10:11]
	s_add_u32 m0, m0, 0x1000
	s_add_u32 s10, s10, 0x1000
	s_addc_u32 s11, s11, 0
	global_load_lds_dwordx4 v140, s[10:11]
	s_add_u32 m0, m0, 0x1000
	s_add_u32 s10, s10, 0x1000
	s_addc_u32 s11, s11, 0
	global_load_lds_dwordx4 v140, s[10:11]
	s_add_u32 m0, m0, 0x1000
	s_lshl_b64 s[10:11], s[14:15], 13
	s_add_u32 s10, s10, s76
	s_addc_u32 s11, s11, s77
	global_load_lds_dwordx4 v140, s[10:11]
	s_add_u32 m0, m0, 0x1000
	s_add_u32 s10, s10, 0x1000
	s_addc_u32 s11, s11, 0
	global_load_lds_dwordx4 v140, s[10:11]
	s_mov_b32 s14, 1
	s_lshl_b64 s[10:11], s[14:15], 14
	s_add_u32 s10, s10, s74
	s_addc_u32 s11, s11, s75
	s_add_u32 m0, s72, 0x6000
	s_nop 0
	global_load_lds_dwordx4 v140, s[10:11]
	s_add_u32 m0, m0, 0x1000
	s_add_u32 s10, s10, 0x1000
	s_addc_u32 s11, s11, 0
	global_load_lds_dwordx4 v140, s[10:11]
	s_add_u32 m0, m0, 0x1000
	s_add_u32 s10, s10, 0x1000
	s_addc_u32 s11, s11, 0
	global_load_lds_dwordx4 v140, s[10:11]
	s_add_u32 m0, m0, 0x1000
	s_add_u32 s10, s10, 0x1000
	s_addc_u32 s11, s11, 0
	global_load_lds_dwordx4 v140, s[10:11]
	s_add_u32 m0, m0, 0x1000
	s_lshl_b64 s[10:11], s[14:15], 13
	s_add_u32 s10, s10, s76
	s_addc_u32 s11, s11, s77
	global_load_lds_dwordx4 v140, s[10:11]
	s_add_u32 m0, m0, 0x1000
	s_add_u32 s10, s10, 0x1000
	s_addc_u32 s11, s11, 0
	global_load_lds_dwordx4 v140, s[10:11]
	s_mov_b32 s14, 2
	s_lshl_b64 s[10:11], s[14:15], 14
	s_add_u32 s10, s10, s74
	s_addc_u32 s11, s11, s75
	s_add_u32 m0, s72, 0xc000
	s_nop 0
	global_load_lds_dwordx4 v140, s[10:11]
	s_add_u32 m0, m0, 0x1000
	s_add_u32 s10, s10, 0x1000
	s_addc_u32 s11, s11, 0
	global_load_lds_dwordx4 v140, s[10:11]
	s_add_u32 m0, m0, 0x1000
	s_add_u32 s10, s10, 0x1000
	s_addc_u32 s11, s11, 0
	global_load_lds_dwordx4 v140, s[10:11]
	s_add_u32 m0, m0, 0x1000
	s_add_u32 s10, s10, 0x1000
	s_addc_u32 s11, s11, 0
	global_load_lds_dwordx4 v140, s[10:11]
	s_add_u32 m0, m0, 0x1000
	s_lshl_b64 s[10:11], s[14:15], 13
	s_add_u32 s10, s10, s76
	s_addc_u32 s11, s11, s77
	global_load_lds_dwordx4 v140, s[10:11]
	s_add_u32 m0, m0, 0x1000
	s_add_u32 s10, s10, 0x1000
	s_addc_u32 s11, s11, 0
	global_load_lds_dwordx4 v140, s[10:11]
	v_and_b32_e32 v2, 0xfffff9f, v6
	v_mul_lo_u32 v160, v2, s0
	v_or_b32_e32 v2, 0x60, v6
	v_lshrrev_b32_e32 v0, 1, v6
	v_and_b32_e32 v3, 0x5f, v6
	v_mul_lo_u32 v161, v2, s0
	v_mov_b32_e32 v2, 0
	s_mov_b32 s7, 0
	v_and_b32_e32 v0, 16, v0
	v_mul_u32_u24_e32 v159, 0x50, v3
	v_mov_b32_e32 v3, v2
	v_mov_b32_e32 v4, v2
	v_mov_b32_e32 v5, v2
	v_mov_b32_e32 v6, v2
	v_mov_b32_e32 v7, v2
	v_mov_b32_e32 v8, v2
	v_mov_b32_e32 v9, v2
	v_mov_b32_e32 v10, v2
	v_mov_b32_e32 v11, v2
	v_mov_b32_e32 v12, v2
	v_mov_b32_e32 v13, v2
	v_mov_b32_e32 v14, v2
	v_mov_b32_e32 v15, v2
	v_mov_b32_e32 v16, v2
	v_mov_b32_e32 v17, v2
	v_mov_b32_e32 v18, v2
	v_mov_b32_e32 v19, v2
	v_mov_b32_e32 v20, v2
	v_mov_b32_e32 v21, v2
	v_mov_b32_e32 v22, v2
	v_mov_b32_e32 v23, v2
	v_mov_b32_e32 v24, v2
	v_mov_b32_e32 v25, v2
	v_mov_b32_e32 v26, v2
	v_mov_b32_e32 v27, v2
	v_mov_b32_e32 v28, v2
	v_mov_b32_e32 v29, v2
	v_mov_b32_e32 v30, v2
	v_mov_b32_e32 v31, v2
	v_mov_b32_e32 v32, v2
	v_mov_b32_e32 v33, v2
	v_mov_b32_e32 v34, v2
	v_mov_b32_e32 v35, v2
	v_mov_b32_e32 v36, v2
	v_mov_b32_e32 v37, v2
	v_mov_b32_e32 v38, v2
	v_mov_b32_e32 v39, v2
	v_mov_b32_e32 v40, v2
	v_mov_b32_e32 v41, v2
	v_mov_b32_e32 v42, v2
	v_mov_b32_e32 v43, v2
	v_mov_b32_e32 v44, v2
	v_mov_b32_e32 v45, v2
	v_mov_b32_e32 v46, v2
	v_mov_b32_e32 v47, v2
	v_mov_b32_e32 v48, v2
	v_mov_b32_e32 v49, v2
	v_mov_b32_e32 v50, v2
	v_mov_b32_e32 v51, v2
	v_mov_b32_e32 v52, v2
	v_mov_b32_e32 v53, v2
	v_mov_b32_e32 v54, v2
	v_mov_b32_e32 v55, v2
	v_mov_b32_e32 v56, v2
	v_mov_b32_e32 v57, v2
	v_mov_b32_e32 v58, v2
	v_mov_b32_e32 v59, v2
	v_mov_b32_e32 v60, v2
	v_mov_b32_e32 v61, v2
	v_mov_b32_e32 v62, v2
	v_mov_b32_e32 v63, v2
	v_mov_b32_e32 v64, v2
	v_mov_b32_e32 v65, v2
	v_mov_b32_e32 v66, v2
	v_mov_b32_e32 v67, v2
	v_mov_b32_e32 v68, v2
	v_mov_b32_e32 v69, v2
	v_mov_b32_e32 v70, v2
	v_mov_b32_e32 v71, v2
	v_mov_b32_e32 v72, v2
	v_mov_b32_e32 v73, v2
	v_mov_b32_e32 v74, v2
	v_mov_b32_e32 v75, v2
	v_mov_b32_e32 v76, v2
	v_mov_b32_e32 v77, v2
	v_mov_b32_e32 v78, v2
	v_mov_b32_e32 v79, v2
	v_mov_b32_e32 v80, v2
	v_mov_b32_e32 v81, v2
	s_waitcnt vmcnt(17)
	v_mov_b32_e32 v82, v2
	v_mov_b32_e32 v83, v2
	v_mov_b32_e32 v84, v2
	v_mov_b32_e32 v85, v2
	s_waitcnt vmcnt(16)
	v_mov_b32_e32 v86, v2
	v_mov_b32_e32 v87, v2
	v_mov_b32_e32 v88, v2
	v_mov_b32_e32 v89, v2
	s_waitcnt vmcnt(15)
	v_mov_b32_e32 v90, v2
	v_mov_b32_e32 v91, v2
	v_mov_b32_e32 v92, v2
	v_mov_b32_e32 v93, v2
	s_waitcnt vmcnt(14)
	v_mov_b32_e32 v94, v2
	v_mov_b32_e32 v95, v2
	v_mov_b32_e32 v96, v2
	v_mov_b32_e32 v97, v2
	v_mov_b32_e32 v98, v2
	v_mov_b32_e32 v99, v2
	v_mov_b32_e32 v100, v2
	v_mov_b32_e32 v101, v2
	v_mov_b32_e32 v102, v2
	v_mov_b32_e32 v103, v2
	v_mov_b32_e32 v104, v2
	v_mov_b32_e32 v105, v2
	v_mov_b32_e32 v106, v2
	v_mov_b32_e32 v107, v2
	v_mov_b32_e32 v108, v2
	v_mov_b32_e32 v109, v2
	v_mov_b32_e32 v110, v2
	v_mov_b32_e32 v111, v2
	v_mov_b32_e32 v112, v2
	v_mov_b32_e32 v113, v2
	v_mov_b32_e32 v114, v2
	v_mov_b32_e32 v115, v2
	v_mov_b32_e32 v116, v2
	v_mov_b32_e32 v117, v2
	v_mov_b32_e32 v118, v2
	v_mov_b32_e32 v119, v2
	v_mov_b32_e32 v120, v2
	v_mov_b32_e32 v121, v2
	v_mov_b32_e32 v122, v2
	v_mov_b32_e32 v123, v2
	v_mov_b32_e32 v124, v2
	v_mov_b32_e32 v125, v2
	v_mov_b32_e32 v126, v2
	v_mov_b32_e32 v127, v2
	v_mov_b32_e32 v128, v2
	v_mov_b32_e32 v129, v2
	s_mov_b32 s7, 0
	s_mov_b32 s13, 0
	v_mov_b32_e32 v138, v132
	v_mov_b32_e32 v139, v133
	s_waitcnt vmcnt(12)
	s_barrier
	ds_read_b128 v[162:165], v138 offset:0
	ds_read_b128 v[228:231], v139 offset:0
	ds_read_b128 v[236:239], v139 offset:2048
	ds_read_b128 v[204:207], v138 offset:2048
	ds_read_b128 v[212:215], v138 offset:4096
	ds_read_b128 v[220:223], v138 offset:6144
	s_movk_i32 s73, 0x6000
	v_mov_b32_e32 v136, v134
	v_mov_b32_e32 v137, v135
	v_add_u32_e32 v138, s73, v132
	v_add_u32_e32 v139, s73, v133
.Lg357_loop:
	s_waitcnt lgkmcnt(0)
	v_mfma_f32_32x32x16_bf16 v[114:129], v[162:165], v[228:231], v[114:129]
	ds_read_b128 v[166:169], v136 offset:0
	ds_read_b128 v[232:235], v137 offset:0
	s_add_i32 s7, s7, 1
	s_add_i32 s14, s7, 2
	s_lshl_b64 s[10:11], s[14:15], 14
	s_add_u32 s10, s10, s74
	s_addc_u32 s11, s11, s75
	v_mfma_f32_32x32x16_bf16 v[98:113], v[162:165], v[236:239], v[98:113]
	ds_read_b128 v[240:243], v137 offset:2048
	ds_read_b128 v[208:211], v136 offset:2048
	v_mfma_f32_32x32x16_bf16 v[82:97], v[204:207], v[228:231], v[82:97]
	ds_read_b128 v[216:219], v136 offset:4096
	ds_read_b128 v[224:227], v136 offset:6144
	v_mfma_f32_32x32x16_bf16 v[66:81], v[204:207], v[236:239], v[66:81]
	v_mfma_f32_32x32x16_bf16 v[50:65], v[212:215], v[228:231], v[50:65]
	v_mfma_f32_32x32x16_bf16 v[34:49], v[212:215], v[236:239], v[34:49]
	v_mfma_f32_32x32x16_bf16 v[18:33], v[220:223], v[228:231], v[18:33]
	v_mfma_f32_32x32x16_bf16 v[2:17], v[220:223], v[236:239], v[2:17]
	s_waitcnt vmcnt(6) lgkmcnt(0)
	s_barrier
	s_add_u32 m0, s13, s72
	s_mov_b32 s13, s73
	s_add_u32 s73, s13, 0x6000
	s_cmp_lt_u32 s73, 0x12000
	s_cselect_b32 s73, s73, 0
	v_mfma_f32_32x32x16_bf16 v[114:129], v[166:169], v[232:235], v[114:129]
	ds_read_b128 v[162:165], v138 offset:0
	ds_read_b128 v[228:231], v139 offset:0
	v_mfma_f32_32x32x16_bf16 v[98:113], v[166:169], v[240:243], v[98:113]
	ds_read_b128 v[236:239], v139 offset:2048
	ds_read_b128 v[204:207], v138 offset:2048
	v_add_u32_e32 v136, s13, v134
	v_add_u32_e32 v137, s13, v135
	v_mfma_f32_32x32x16_bf16 v[82:97], v[208:211], v[232:235], v[82:97]
	ds_read_b128 v[212:215], v138 offset:4096
	ds_read_b128 v[220:223], v138 offset:6144
	v_mfma_f32_32x32x16_bf16 v[66:81], v[208:211], v[240:243], v[66:81]
	global_load_lds_dwordx4 v140, s[10:11]
	s_add_u32 m0, m0, 0x1000
	s_add_u32 s10, s10, 0x1000
	s_addc_u32 s11, s11, 0
	v_add_u32_e32 v138, s73, v132
	v_add_u32_e32 v139, s73, v133
	v_mfma_f32_32x32x16_bf16 v[50:65], v[216:219], v[232:235], v[50:65]
	global_load_lds_dwordx4 v140, s[10:11]
	s_add_u32 m0, m0, 0x1000
	s_add_u32 s10, s10, 0x1000
	s_addc_u32 s11, s11, 0
	v_mfma_f32_32x32x16_bf16 v[34:49], v[216:219], v[240:243], v[34:49]
	global_load_lds_dwordx4 v140, s[10:11]
	s_add_u32 m0, m0, 0x1000
	s_add_u32 s10, s10, 0x1000
	s_addc_u32 s11, s11, 0
	v_mfma_f32_32x32x16_bf16 v[18:33], v[224:227], v[232:235], v[18:33]
	global_load_lds_dwordx4 v140, s[10:11]
	s_add_u32 m0, m0, 0x1000
	s_lshl_b64 s[10:11], s[14:15], 13
	s_add_u32 s10, s10, s76
	s_addc_u32 s11, s11, s77
	v_mfma_f32_32x32x16_bf16 v[2:17], v[224:227], v[240:243], v[2:17]
	global_load_lds_dwordx4 v140, s[10:11]
	s_add_u32 m0, m0, 0x1000
	s_add_u32 s10, s10, 0x1000
	s_addc_u32 s11, s11, 0
	s_nop 0
	global_load_lds_dwordx4 v140, s[10:11]
	s_cmp_lg_u32 s7, 29
	s_cbranch_scc1 .Lg357_loop
	s_waitcnt lgkmcnt(0)
	v_mfma_f32_32x32x16_bf16 v[114:129], v[162:165], v[228:231], v[114:129]
	ds_read_b128 v[166:169], v136 offset:0
	ds_read_b128 v[232:235], v137 offset:0
	s_add_i32 s7, s7, 1
	v_mfma_f32_32x32x16_bf16 v[98:113], v[162:165], v[236:239], v[98:113]
	ds_read_b128 v[240:243], v137 offset:2048
	ds_read_b128 v[208:211], v136 offset:2048
	v_mfma_f32_32x32x16_bf16 v[82:97], v[204:207], v[228:231], v[82:97]
	ds_read_b128 v[216:219], v136 offset:4096
	ds_read_b128 v[224:227], v136 offset:6144
	v_mfma_f32_32x32x16_bf16 v[66:81], v[204:207], v[236:239], v[66:81]
	v_mfma_f32_32x32x16_bf16 v[50:65], v[212:215], v[228:231], v[50:65]
	v_mfma_f32_32x32x16_bf16 v[34:49], v[212:215], v[236:239], v[34:49]
	v_mfma_f32_32x32x16_bf16 v[18:33], v[220:223], v[228:231], v[18:33]
	v_mfma_f32_32x32x16_bf16 v[2:17], v[220:223], v[236:239], v[2:17]
	s_waitcnt vmcnt(6) lgkmcnt(0)
	s_barrier
	s_mov_b32 s13, s73
	s_add_u32 s73, s13, 0x6000
	s_cmp_lt_u32 s73, 0x12000
	s_cselect_b32 s73, s73, 0
	v_mfma_f32_32x32x16_bf16 v[114:129], v[166:169], v[232:235], v[114:129]
	ds_read_b128 v[162:165], v138 offset:0
	ds_read_b128 v[228:231], v139 offset:0
	v_mfma_f32_32x32x16_bf16 v[98:113], v[166:169], v[240:243], v[98:113]
	ds_read_b128 v[236:239], v139 offset:2048
	ds_read_b128 v[204:207], v138 offset:2048
	v_add_u32_e32 v136, s13, v134
	v_add_u32_e32 v137, s13, v135
	v_mfma_f32_32x32x16_bf16 v[82:97], v[208:211], v[232:235], v[82:97]
	ds_read_b128 v[212:215], v138 offset:4096
	ds_read_b128 v[220:223], v138 offset:6144
	v_mfma_f32_32x32x16_bf16 v[66:81], v[208:211], v[240:243], v[66:81]
	v_add_u32_e32 v138, s73, v132
	v_add_u32_e32 v139, s73, v133
	v_mfma_f32_32x32x16_bf16 v[50:65], v[216:219], v[232:235], v[50:65]
	v_mfma_f32_32x32x16_bf16 v[34:49], v[216:219], v[240:243], v[34:49]
	v_mfma_f32_32x32x16_bf16 v[18:33], v[224:227], v[232:235], v[18:33]
	v_mfma_f32_32x32x16_bf16 v[2:17], v[224:227], v[240:243], v[2:17]
	s_waitcnt lgkmcnt(0)
	v_mfma_f32_32x32x16_bf16 v[114:129], v[162:165], v[228:231], v[114:129]
	ds_read_b128 v[166:169], v136 offset:0
	ds_read_b128 v[232:235], v137 offset:0
	s_add_i32 s7, s7, 1
	v_mfma_f32_32x32x16_bf16 v[98:113], v[162:165], v[236:239], v[98:113]
	ds_read_b128 v[240:243], v137 offset:2048
	ds_read_b128 v[208:211], v136 offset:2048
	v_mfma_f32_32x32x16_bf16 v[82:97], v[204:207], v[228:231], v[82:97]
	ds_read_b128 v[216:219], v136 offset:4096
	ds_read_b128 v[224:227], v136 offset:6144
	v_mfma_f32_32x32x16_bf16 v[66:81], v[204:207], v[236:239], v[66:81]
	v_mfma_f32_32x32x16_bf16 v[50:65], v[212:215], v[228:231], v[50:65]
	v_mfma_f32_32x32x16_bf16 v[34:49], v[212:215], v[236:239], v[34:49]
	v_mfma_f32_32x32x16_bf16 v[18:33], v[220:223], v[228:231], v[18:33]
	v_mfma_f32_32x32x16_bf16 v[2:17], v[220:223], v[236:239], v[2:17]
	s_waitcnt vmcnt(0) lgkmcnt(0)
	s_barrier
	s_mov_b32 s13, s73
	s_add_u32 s73, s13, 0x6000
	s_cmp_lt_u32 s73, 0x12000
	s_cselect_b32 s73, s73, 0
	v_mfma_f32_32x32x16_bf16 v[114:129], v[166:169], v[232:235], v[114:129]
	ds_read_b128 v[162:165], v138 offset:0
	ds_read_b128 v[228:231], v139 offset:0
	v_mfma_f32_32x32x16_bf16 v[98:113], v[166:169], v[240:243], v[98:113]
	ds_read_b128 v[236:239], v139 offset:2048
	ds_read_b128 v[204:207], v138 offset:2048
	v_add_u32_e32 v136, s13, v134
	v_add_u32_e32 v137, s13, v135
	v_mfma_f32_32x32x16_bf16 v[82:97], v[208:211], v[232:235], v[82:97]
	ds_read_b128 v[212:215], v138 offset:4096
	ds_read_b128 v[220:223], v138 offset:6144
	v_mfma_f32_32x32x16_bf16 v[66:81], v[208:211], v[240:243], v[66:81]
	v_add_u32_e32 v138, s73, v132
	v_add_u32_e32 v139, s73, v133
	v_mfma_f32_32x32x16_bf16 v[50:65], v[216:219], v[232:235], v[50:65]
	v_mfma_f32_32x32x16_bf16 v[34:49], v[216:219], v[240:243], v[34:49]
	v_mfma_f32_32x32x16_bf16 v[18:33], v[224:227], v[232:235], v[18:33]
	v_mfma_f32_32x32x16_bf16 v[2:17], v[224:227], v[240:243], v[2:17]
	s_waitcnt lgkmcnt(0)
	v_mfma_f32_32x32x16_bf16 v[114:129], v[162:165], v[228:231], v[114:129]
	ds_read_b128 v[166:169], v136 offset:0
	ds_read_b128 v[232:235], v137 offset:0
	s_add_i32 s7, s7, 1
	v_mfma_f32_32x32x16_bf16 v[98:113], v[162:165], v[236:239], v[98:113]
	ds_read_b128 v[240:243], v137 offset:2048
	ds_read_b128 v[208:211], v136 offset:2048
	v_mfma_f32_32x32x16_bf16 v[82:97], v[204:207], v[228:231], v[82:97]
	ds_read_b128 v[216:219], v136 offset:4096
	ds_read_b128 v[224:227], v136 offset:6144
	v_mfma_f32_32x32x16_bf16 v[66:81], v[204:207], v[236:239], v[66:81]
	v_mfma_f32_32x32x16_bf16 v[50:65], v[212:215], v[228:231], v[50:65]
	v_mfma_f32_32x32x16_bf16 v[34:49], v[212:215], v[236:239], v[34:49]
	v_mfma_f32_32x32x16_bf16 v[18:33], v[220:223], v[228:231], v[18:33]
	v_mfma_f32_32x32x16_bf16 v[2:17], v[220:223], v[236:239], v[2:17]
	s_waitcnt lgkmcnt(0)
	v_mfma_f32_32x32x16_bf16 v[114:129], v[166:169], v[232:235], v[114:129]
	v_mfma_f32_32x32x16_bf16 v[98:113], v[166:169], v[240:243], v[98:113]
	v_mfma_f32_32x32x16_bf16 v[82:97], v[208:211], v[232:235], v[82:97]
	v_mfma_f32_32x32x16_bf16 v[66:81], v[208:211], v[240:243], v[66:81]
	v_mfma_f32_32x32x16_bf16 v[50:65], v[216:219], v[232:235], v[50:65]
	v_mfma_f32_32x32x16_bf16 v[34:49], v[216:219], v[240:243], v[34:49]
	v_mfma_f32_32x32x16_bf16 v[18:33], v[224:227], v[232:235], v[18:33]
	v_mfma_f32_32x32x16_bf16 v[2:17], v[224:227], v[240:243], v[2:17]
	s_mov_b32 s14, 31
	s_lshl_b64 s[10:11], s[14:15], 13
	s_movk_i32 s13, 0x7800
	s_movk_i32 s72, 0x6000
	s_mov_b32 s73, 0xc000
	s_movk_i32 s74, 0x104
	s_mov_b32 s75, 0x42ce8ed0
	s_mov_b32 s76, 0xbfb8aa3b
	s_mov_b32 s77, 0x1d730000
	v_mov_b32_e32 v0, v171
	s_barrier
	s_waitcnt vmcnt(4)
	v_lshrrev_b32_e32 v130, 1, v0
	v_and_b32_e32 v130, 0xfffffc0, v130
	v_lshrrev_b32_e32 v131, 3, v0
	v_and_or_b32 v130, v131, 4, v130
	v_and_b32_e32 v0, 0x5f, v0
	v_mul_lo_u32 v130, v130, s53
	v_lshl_add_u32 v0, v0, 2, v130
	s_barrier
	ds_write2_b32 v0, v114, v98 offset1:32
	ds_write2_b32 v0, v115, v99 offset0:132 offset1:164
	v_add_u32_e32 v98, 0x400, v0
	ds_write2_b32 v98, v116, v100 offset0:8 offset1:40
	ds_write2_b32 v98, v117, v101 offset0:140 offset1:172
	v_add_u32_e32 v98, 0x1000, v0
	ds_write2_b32 v98, v118, v102 offset0:32 offset1:64
	ds_write2_b32 v98, v119, v103 offset0:164 offset1:196
	v_add_u32_e32 v98, 0x1400, v0
	ds_write2_b32 v98, v120, v104 offset0:40 offset1:72
	ds_write2_b32 v98, v121, v105 offset0:172 offset1:204
	v_add_u32_e32 v98, 0x2000, v0
	ds_write2_b32 v98, v122, v106 offset0:64 offset1:96
	ds_write2_b32 v98, v123, v107 offset0:196 offset1:228
	v_add_u32_e32 v98, 0x2400, v0
	ds_write2_b32 v98, v124, v108 offset0:72 offset1:104
	ds_write2_b32 v98, v125, v109 offset0:204 offset1:236
	v_add_u32_e32 v98, 0x3000, v0
	ds_write2_b32 v98, v126, v110 offset0:96 offset1:128
	v_add_u32_e32 v98, 0x3200, v0
	ds_write2_b32 v98, v127, v111 offset0:100 offset1:132
	v_add_u32_e32 v98, 0x3400, v0
	ds_write2_b32 v98, v128, v112 offset0:104 offset1:136
	v_add_u32_e32 v98, 0x3600, v0
	ds_write2_b32 v98, v129, v113 offset0:108 offset1:140
	v_add_u32_e32 v98, 0x4000, v0
	ds_write2_b32 v98, v82, v66 offset0:128 offset1:160
	v_add_u32_e32 v66, 0x4400, v0
	ds_write2_b32 v66, v83, v67 offset0:4 offset1:36
	ds_write2_b32 v66, v84, v68 offset0:136 offset1:168
	v_add_u32_e32 v66, 0x4800, v0
	ds_write2_b32 v66, v85, v69 offset0:12 offset1:44
	v_add_u32_e32 v66, 0x5000, v0
	s_lshl_b32 s13, s9, 8
	ds_write2_b32 v66, v86, v70 offset0:160 offset1:192
	v_add_u32_e32 v66, 0x5400, v0
	s_lshl_b32 s34, s6, 7
	ds_write2_b32 v66, v87, v71 offset0:36 offset1:68
	ds_write2_b32 v66, v88, v72 offset0:168 offset1:200
	v_add_u32_e32 v66, 0x5800, v0
	s_add_i32 s6, s13, 0xffffe000
	ds_write2_b32 v66, v89, v73 offset0:44 offset1:76
	v_add_u32_e32 v66, 0x6000, v0
	s_lshr_b32 s6, s6, 12
	ds_write2_b32 v66, v90, v74 offset0:192 offset1:224
	v_add_u32_e32 v66, 0x6400, v0
	s_mulk_i32 s6, 0x1800
	ds_write2_b32 v66, v91, v75 offset0:68 offset1:100
	ds_write2_b32 v66, v92, v76 offset0:200 offset1:232
	v_add_u32_e32 v66, 0x6800, v0
	s_addk_i32 s6, 0x1800
	ds_write2_b32 v66, v93, v77 offset0:76 offset1:108
	v_add_u32_e32 v66, 0x7200, v0
	s_cmp_gt_u32 s8, 31
	ds_write2_b32 v66, v94, v78 offset0:96 offset1:128
	v_add_u32_e32 v66, 0x7400, v0
	s_cselect_b32 s14, s6, 0
	ds_write2_b32 v66, v95, v79 offset0:100 offset1:132
	v_add_u32_e32 v66, 0x7600, v0
	v_add_u32_e32 v0, 0x7800, v0
	v_mov_b32_e32 v76, v171
	s_lshl_b64 s[6:7], s[14:15], 2
	ds_write2_b32 v66, v96, v80 offset0:104 offset1:136
	ds_write2_b32 v0, v97, v81 offset0:108 offset1:140
	s_waitcnt lgkmcnt(0)
	s_barrier
	s_add_u32 s6, s61, s6
	v_lshlrev_b32_e32 v0, 3, v76
	v_and_b32_e32 v0, 0x78, v0
	s_addc_u32 s7, s79, s7
	v_or_b32_e32 v0, s34, v0
	s_add_u32 s8, s6, 0x1d642000
	s_addc_u32 s9, s7, 0
	v_lshlrev_b64 v[74:75], 2, v[0:1]
	v_lshl_add_u64 v[70:71], s[8:9], 0, v[74:75]
	global_load_dwordx4 v[66:69], v[70:71], off offset:16
	s_nop 0
	global_load_dwordx4 v[70:73], v[70:71], off
	v_ashrrev_i32_e32 v90, 4, v76
	v_lshl_add_u64 v[82:83], s[56:57], 0, v[74:75]
	v_mul_lo_u32 v74, v90, s53
	v_and_b32_e32 v75, 15, v76
	s_mov_b32 s14, 0
	v_lshl_add_u32 v91, v75, 5, v74
	v_lshlrev_b32_e32 v92, 1, v90
	s_branch .LBB0_360

.LBB0_431:
	s_lshr_b32 s6, s79, 3
	s_and_b32 s8, s79, 56
	v_readlane_b32 s0, v252, 42
	s_and_b32 s7, s79, 7
	s_or_b32 s43, s8, s0
	s_and_b32 s40, s6, 56
	v_mov_b32_e32 v6, v171
	s_or_b32 s42, s40, s7
	s_lshl_b32 s6, s43, 19
	v_lshlrev_b32_e32 v2, 3, v6
	s_add_u32 s6, s98, s6
	v_ashrrev_i32_e32 v3, 31, v2
	s_addc_u32 s7, s99, 0
	v_lshlrev_b64 v[4:5], 1, v[2:3]
	v_lshl_add_u64 v[154:155], s[6:7], 0, v[4:5]
	s_mov_b64 s[74:75], s[6:7]
	s_lshl_b32 s6, s42, 18
	s_add_u32 s6, s92, s6
	s_addc_u32 s7, s93, 0
	v_lshrrev_b32_e32 v3, 2, v6
	v_and_b32_e32 v0, 24, v2
	v_lshl_add_u64 v[156:157], s[6:7], 0, v[4:5]
	s_mov_b64 s[76:77], s[6:7]
	v_mad_u64_u32 v[158:159], s[6:7], v3, 40, v[0:1]
	s_movk_i32 s0, 0x50
	v_and_b32_e32 v2, 0x30, v6
	v_xor_b32_e32 v140, v4, v2
	v_xor_b32_e32 v154, v154, v2
	v_xor_b32_e32 v156, v156, v2
	v_and_b32_e32 v130, 31, v6
	v_lshlrev_b32_e32 v130, 6, v130
	v_lshrrev_b32_e32 v131, 2, v6
	v_and_b32_e32 v131, 3, v131
	v_bfe_u32 v133, v6, 5, 1
	v_xor_b32_e32 v131, v131, v133
	v_lshl_or_b32 v130, v131, 4, v130
	v_lshrrev_b32_e32 v131, 7, v6
	v_lshl_or_b32 v132, v131, 13, v130
	v_bfe_u32 v131, v6, 6, 1
	v_lshl_or_b32 v133, v131, 12, v130
	v_or_b32_e32 v133, 0x4000, v133
	v_xor_b32_e32 v134, 32, v132
	v_xor_b32_e32 v135, 32, v133
	v_lshrrev_b32_e32 v131, 6, v6
	s_nop 1
	v_readfirstlane_b32 s72, v131
	s_nop 3
	s_lshl_b32 s72, s72, 10
	s_waitcnt lgkmcnt(0)
	s_barrier
	s_mov_b32 s14, 0
	s_lshl_b64 s[12:13], s[14:15], 14
	s_add_u32 s12, s12, s74
	s_addc_u32 s13, s13, s75
	s_add_u32 m0, s72, 0x0
	s_nop 0
	global_load_lds_dwordx4 v140, s[12:13]
	s_add_u32 m0, m0, 0x1000
	s_add_u32 s12, s12, 0x1000
	s_addc_u32 s13, s13, 0
	global_load_lds_dwordx4 v140, s[12:13]
	s_add_u32 m0, m0, 0x1000
	s_add_u32 s12, s12, 0x1000
	s_addc_u32 s13, s13, 0
	global_load_lds_dwordx4 v140, s[12:13]
	s_add_u32 m0, m0, 0x1000
	s_add_u32 s12, s12, 0x1000
	s_addc_u32 s13, s13, 0
	global_load_lds_dwordx4 v140, s[12:13]
	s_add_u32 m0, m0, 0x1000
	s_lshl_b64 s[12:13], s[14:15], 13
	s_add_u32 s12, s12, s76
	s_addc_u32 s13, s13, s77
	global_load_lds_dwordx4 v140, s[12:13]
	s_add_u32 m0, m0, 0x1000
	s_add_u32 s12, s12, 0x1000
	s_addc_u32 s13, s13, 0
	global_load_lds_dwordx4 v140, s[12:13]
	s_mov_b32 s14, 1
	s_lshl_b64 s[12:13], s[14:15], 14
	s_add_u32 s12, s12, s74
	s_addc_u32 s13, s13, s75
	s_add_u32 m0, s72, 0x6000
	s_nop 0
	global_load_lds_dwordx4 v140, s[12:13]
	s_add_u32 m0, m0, 0x1000
	s_add_u32 s12, s12, 0x1000
	s_addc_u32 s13, s13, 0
	global_load_lds_dwordx4 v140, s[12:13]
	s_add_u32 m0, m0, 0x1000
	s_add_u32 s12, s12, 0x1000
	s_addc_u32 s13, s13, 0
	global_load_lds_dwordx4 v140, s[12:13]
	s_add_u32 m0, m0, 0x1000
	s_add_u32 s12, s12, 0x1000
	s_addc_u32 s13, s13, 0
	global_load_lds_dwordx4 v140, s[12:13]
	s_add_u32 m0, m0, 0x1000
	s_lshl_b64 s[12:13], s[14:15], 13
	s_add_u32 s12, s12, s76
	s_addc_u32 s13, s13, s77
	global_load_lds_dwordx4 v140, s[12:13]
	s_add_u32 m0, m0, 0x1000
	s_add_u32 s12, s12, 0x1000
	s_addc_u32 s13, s13, 0
	global_load_lds_dwordx4 v140, s[12:13]
	s_mov_b32 s14, 2
	s_lshl_b64 s[12:13], s[14:15], 14
	s_add_u32 s12, s12, s74
	s_addc_u32 s13, s13, s75
	s_add_u32 m0, s72, 0xc000
	s_nop 0
	global_load_lds_dwordx4 v140, s[12:13]
	s_add_u32 m0, m0, 0x1000
	s_add_u32 s12, s12, 0x1000
	s_addc_u32 s13, s13, 0
	global_load_lds_dwordx4 v140, s[12:13]
	s_add_u32 m0, m0, 0x1000
	s_add_u32 s12, s12, 0x1000
	s_addc_u32 s13, s13, 0
	global_load_lds_dwordx4 v140, s[12:13]
	s_add_u32 m0, m0, 0x1000
	s_add_u32 s12, s12, 0x1000
	s_addc_u32 s13, s13, 0
	global_load_lds_dwordx4 v140, s[12:13]
	s_add_u32 m0, m0, 0x1000
	s_lshl_b64 s[12:13], s[14:15], 13
	s_add_u32 s12, s12, s76
	s_addc_u32 s13, s13, s77
	global_load_lds_dwordx4 v140, s[12:13]
	s_add_u32 m0, m0, 0x1000
	s_add_u32 s12, s12, 0x1000
	s_addc_u32 s13, s13, 0
	global_load_lds_dwordx4 v140, s[12:13]
	v_and_b32_e32 v2, 0xfffff9f, v6
	v_mul_lo_u32 v160, v2, s0
	v_or_b32_e32 v2, 0x60, v6
	v_lshrrev_b32_e32 v0, 1, v6
	v_and_b32_e32 v3, 0x5f, v6
	v_mul_lo_u32 v161, v2, s0
	v_mov_b32_e32 v2, 0
	s_mov_b32 s6, 0
	v_and_b32_e32 v0, 16, v0
	v_mul_u32_u24_e32 v159, 0x50, v3
	v_mov_b32_e32 v3, v2
	v_mov_b32_e32 v4, v2
	v_mov_b32_e32 v5, v2
	v_mov_b32_e32 v6, v2
	v_mov_b32_e32 v7, v2
	v_mov_b32_e32 v8, v2
	v_mov_b32_e32 v9, v2
	v_mov_b32_e32 v10, v2
	v_mov_b32_e32 v11, v2
	v_mov_b32_e32 v12, v2
	v_mov_b32_e32 v13, v2
	v_mov_b32_e32 v14, v2
	v_mov_b32_e32 v15, v2
	v_mov_b32_e32 v16, v2
	v_mov_b32_e32 v17, v2
	v_mov_b32_e32 v18, v2
	v_mov_b32_e32 v19, v2
	v_mov_b32_e32 v20, v2
	v_mov_b32_e32 v21, v2
	v_mov_b32_e32 v22, v2
	v_mov_b32_e32 v23, v2
	v_mov_b32_e32 v24, v2
	v_mov_b32_e32 v25, v2
	v_mov_b32_e32 v26, v2
	v_mov_b32_e32 v27, v2
	v_mov_b32_e32 v28, v2
	v_mov_b32_e32 v29, v2
	v_mov_b32_e32 v30, v2
	v_mov_b32_e32 v31, v2
	v_mov_b32_e32 v32, v2
	v_mov_b32_e32 v33, v2
	v_mov_b32_e32 v34, v2
	v_mov_b32_e32 v35, v2
	v_mov_b32_e32 v36, v2
	v_mov_b32_e32 v37, v2
	v_mov_b32_e32 v38, v2
	v_mov_b32_e32 v39, v2
	v_mov_b32_e32 v40, v2
	v_mov_b32_e32 v41, v2
	v_mov_b32_e32 v42, v2
	v_mov_b32_e32 v43, v2
	v_mov_b32_e32 v44, v2
	v_mov_b32_e32 v45, v2
	v_mov_b32_e32 v46, v2
	v_mov_b32_e32 v47, v2
	v_mov_b32_e32 v48, v2
	v_mov_b32_e32 v49, v2
	v_mov_b32_e32 v50, v2
	v_mov_b32_e32 v51, v2
	v_mov_b32_e32 v52, v2
	v_mov_b32_e32 v53, v2
	v_mov_b32_e32 v54, v2
	v_mov_b32_e32 v55, v2
	v_mov_b32_e32 v56, v2
	v_mov_b32_e32 v57, v2
	v_mov_b32_e32 v58, v2
	v_mov_b32_e32 v59, v2
	v_mov_b32_e32 v60, v2
	v_mov_b32_e32 v61, v2
	v_mov_b32_e32 v62, v2
	v_mov_b32_e32 v63, v2
	v_mov_b32_e32 v64, v2
	v_mov_b32_e32 v65, v2
	v_mov_b32_e32 v66, v2
	v_mov_b32_e32 v67, v2
	v_mov_b32_e32 v68, v2
	v_mov_b32_e32 v69, v2
	v_mov_b32_e32 v70, v2
	v_mov_b32_e32 v71, v2
	v_mov_b32_e32 v72, v2
	v_mov_b32_e32 v73, v2
	v_mov_b32_e32 v74, v2
	v_mov_b32_e32 v75, v2
	v_mov_b32_e32 v76, v2
	v_mov_b32_e32 v77, v2
	v_mov_b32_e32 v78, v2
	v_mov_b32_e32 v79, v2
	v_mov_b32_e32 v80, v2
	v_mov_b32_e32 v81, v2
	s_waitcnt vmcnt(17)
	v_mov_b32_e32 v82, v2
	v_mov_b32_e32 v83, v2
	v_mov_b32_e32 v84, v2
	v_mov_b32_e32 v85, v2
	s_waitcnt vmcnt(16)
	v_mov_b32_e32 v86, v2
	v_mov_b32_e32 v87, v2
	v_mov_b32_e32 v88, v2
	v_mov_b32_e32 v89, v2
	s_waitcnt vmcnt(15)
	v_mov_b32_e32 v90, v2
	v_mov_b32_e32 v91, v2
	v_mov_b32_e32 v92, v2
	v_mov_b32_e32 v93, v2
	s_waitcnt vmcnt(14)
	v_mov_b32_e32 v94, v2
	v_mov_b32_e32 v95, v2
	v_mov_b32_e32 v96, v2
	v_mov_b32_e32 v97, v2
	v_mov_b32_e32 v98, v2
	v_mov_b32_e32 v99, v2
	v_mov_b32_e32 v100, v2
	v_mov_b32_e32 v101, v2
	v_mov_b32_e32 v102, v2
	v_mov_b32_e32 v103, v2
	v_mov_b32_e32 v104, v2
	v_mov_b32_e32 v105, v2
	v_mov_b32_e32 v106, v2
	v_mov_b32_e32 v107, v2
	v_mov_b32_e32 v108, v2
	v_mov_b32_e32 v109, v2
	v_mov_b32_e32 v110, v2
	v_mov_b32_e32 v111, v2
	v_mov_b32_e32 v112, v2
	v_mov_b32_e32 v113, v2
	v_mov_b32_e32 v114, v2
	v_mov_b32_e32 v115, v2
	v_mov_b32_e32 v116, v2
	v_mov_b32_e32 v117, v2
	v_mov_b32_e32 v118, v2
	v_mov_b32_e32 v119, v2
	v_mov_b32_e32 v120, v2
	v_mov_b32_e32 v121, v2
	v_mov_b32_e32 v122, v2
	v_mov_b32_e32 v123, v2
	v_mov_b32_e32 v124, v2
	v_mov_b32_e32 v125, v2
	v_mov_b32_e32 v126, v2
	v_mov_b32_e32 v127, v2
	v_mov_b32_e32 v128, v2
	v_mov_b32_e32 v129, v2
	s_waitcnt lgkmcnt(0)
	s_mov_b32 s6, 0
	s_mov_b32 s7, 0
	v_mov_b32_e32 v138, v132
	v_mov_b32_e32 v139, v133
	s_waitcnt vmcnt(12)
	s_barrier
	ds_read_b128 v[162:165], v138 offset:0
	ds_read_b128 v[228:231], v139 offset:0
	ds_read_b128 v[236:239], v139 offset:2048
	ds_read_b128 v[204:207], v138 offset:2048
	ds_read_b128 v[212:215], v138 offset:4096
	ds_read_b128 v[220:223], v138 offset:6144
	s_movk_i32 s73, 0x6000
	v_mov_b32_e32 v136, v134
	v_mov_b32_e32 v137, v135
	v_add_u32_e32 v138, s73, v132
	v_add_u32_e32 v139, s73, v133
.Lg432_loop:
	s_waitcnt lgkmcnt(0)
	v_mfma_f32_32x32x16_bf16 v[114:129], v[162:165], v[228:231], v[114:129]
	ds_read_b128 v[166:169], v136 offset:0
	ds_read_b128 v[232:235], v137 offset:0
	s_add_i32 s6, s6, 1
	s_add_i32 s14, s6, 2
	s_lshl_b64 s[12:13], s[14:15], 14
	s_add_u32 s12, s12, s74
	s_addc_u32 s13, s13, s75
	v_mfma_f32_32x32x16_bf16 v[98:113], v[162:165], v[236:239], v[98:113]
	ds_read_b128 v[240:243], v137 offset:2048
	ds_read_b128 v[208:211], v136 offset:2048
	v_mfma_f32_32x32x16_bf16 v[82:97], v[204:207], v[228:231], v[82:97]
	ds_read_b128 v[216:219], v136 offset:4096
	ds_read_b128 v[224:227], v136 offset:6144
	v_mfma_f32_32x32x16_bf16 v[66:81], v[204:207], v[236:239], v[66:81]
	v_mfma_f32_32x32x16_bf16 v[50:65], v[212:215], v[228:231], v[50:65]
	v_mfma_f32_32x32x16_bf16 v[34:49], v[212:215], v[236:239], v[34:49]
	v_mfma_f32_32x32x16_bf16 v[18:33], v[220:223], v[228:231], v[18:33]
	v_mfma_f32_32x32x16_bf16 v[2:17], v[220:223], v[236:239], v[2:17]
	s_waitcnt vmcnt(6) lgkmcnt(0)
	s_barrier
	s_add_u32 m0, s7, s72
	s_mov_b32 s7, s73
	s_add_u32 s73, s7, 0x6000
	s_cmp_lt_u32 s73, 0x12000
	s_cselect_b32 s73, s73, 0
	v_mfma_f32_32x32x16_bf16 v[114:129], v[166:169], v[232:235], v[114:129]
	ds_read_b128 v[162:165], v138 offset:0
	ds_read_b128 v[228:231], v139 offset:0
	v_mfma_f32_32x32x16_bf16 v[98:113], v[166:169], v[240:243], v[98:113]
	ds_read_b128 v[236:239], v139 offset:2048
	ds_read_b128 v[204:207], v138 offset:2048
	v_add_u32_e32 v136, s7, v134
	v_add_u32_e32 v137, s7, v135
	v_mfma_f32_32x32x16_bf16 v[82:97], v[208:211], v[232:235], v[82:97]
	ds_read_b128 v[212:215], v138 offset:4096
	ds_read_b128 v[220:223], v138 offset:6144
	v_mfma_f32_32x32x16_bf16 v[66:81], v[208:211], v[240:243], v[66:81]
	global_load_lds_dwordx4 v140, s[12:13]
	s_add_u32 m0, m0, 0x1000
	s_add_u32 s12, s12, 0x1000
	s_addc_u32 s13, s13, 0
	v_add_u32_e32 v138, s73, v132
	v_add_u32_e32 v139, s73, v133
	v_mfma_f32_32x32x16_bf16 v[50:65], v[216:219], v[232:235], v[50:65]
	global_load_lds_dwordx4 v140, s[12:13]
	s_add_u32 m0, m0, 0x1000
	s_add_u32 s12, s12, 0x1000
	s_addc_u32 s13, s13, 0
	v_mfma_f32_32x32x16_bf16 v[34:49], v[216:219], v[240:243], v[34:49]
	global_load_lds_dwordx4 v140, s[12:13]
	s_add_u32 m0, m0, 0x1000
	s_add_u32 s12, s12, 0x1000
	s_addc_u32 s13, s13, 0
	v_mfma_f32_32x32x16_bf16 v[18:33], v[224:227], v[232:235], v[18:33]
	global_load_lds_dwordx4 v140, s[12:13]
	s_add_u32 m0, m0, 0x1000
	s_lshl_b64 s[12:13], s[14:15], 13
	s_add_u32 s12, s12, s76
	s_addc_u32 s13, s13, s77
	v_mfma_f32_32x32x16_bf16 v[2:17], v[224:227], v[240:243], v[2:17]
	global_load_lds_dwordx4 v140, s[12:13]
	s_add_u32 m0, m0, 0x1000
	s_add_u32 s12, s12, 0x1000
	s_addc_u32 s13, s13, 0
	s_nop 0
	global_load_lds_dwordx4 v140, s[12:13]
	s_cmp_lg_u32 s6, 29
	s_cbranch_scc1 .Lg432_loop
	s_waitcnt lgkmcnt(0)
	v_mfma_f32_32x32x16_bf16 v[114:129], v[162:165], v[228:231], v[114:129]
	ds_read_b128 v[166:169], v136 offset:0
	ds_read_b128 v[232:235], v137 offset:0
	s_add_i32 s6, s6, 1
	v_mfma_f32_32x32x16_bf16 v[98:113], v[162:165], v[236:239], v[98:113]
	ds_read_b128 v[240:243], v137 offset:2048
	ds_read_b128 v[208:211], v136 offset:2048
	v_mfma_f32_32x32x16_bf16 v[82:97], v[204:207], v[228:231], v[82:97]
	ds_read_b128 v[216:219], v136 offset:4096
	ds_read_b128 v[224:227], v136 offset:6144
	v_mfma_f32_32x32x16_bf16 v[66:81], v[204:207], v[236:239], v[66:81]
	v_mfma_f32_32x32x16_bf16 v[50:65], v[212:215], v[228:231], v[50:65]
	v_mfma_f32_32x32x16_bf16 v[34:49], v[212:215], v[236:239], v[34:49]
	v_mfma_f32_32x32x16_bf16 v[18:33], v[220:223], v[228:231], v[18:33]
	v_mfma_f32_32x32x16_bf16 v[2:17], v[220:223], v[236:239], v[2:17]
	s_waitcnt vmcnt(6) lgkmcnt(0)
	s_barrier
	s_mov_b32 s7, s73
	s_add_u32 s73, s7, 0x6000
	s_cmp_lt_u32 s73, 0x12000
	s_cselect_b32 s73, s73, 0
	v_mfma_f32_32x32x16_bf16 v[114:129], v[166:169], v[232:235], v[114:129]
	ds_read_b128 v[162:165], v138 offset:0
	ds_read_b128 v[228:231], v139 offset:0
	v_mfma_f32_32x32x16_bf16 v[98:113], v[166:169], v[240:243], v[98:113]
	ds_read_b128 v[236:239], v139 offset:2048
	ds_read_b128 v[204:207], v138 offset:2048
	v_add_u32_e32 v136, s7, v134
	v_add_u32_e32 v137, s7, v135
	v_mfma_f32_32x32x16_bf16 v[82:97], v[208:211], v[232:235], v[82:97]
	ds_read_b128 v[212:215], v138 offset:4096
	ds_read_b128 v[220:223], v138 offset:6144
	v_mfma_f32_32x32x16_bf16 v[66:81], v[208:211], v[240:243], v[66:81]
	v_add_u32_e32 v138, s73, v132
	v_add_u32_e32 v139, s73, v133
	v_mfma_f32_32x32x16_bf16 v[50:65], v[216:219], v[232:235], v[50:65]
	v_mfma_f32_32x32x16_bf16 v[34:49], v[216:219], v[240:243], v[34:49]
	v_mfma_f32_32x32x16_bf16 v[18:33], v[224:227], v[232:235], v[18:33]
	v_mfma_f32_32x32x16_bf16 v[2:17], v[224:227], v[240:243], v[2:17]
	s_waitcnt lgkmcnt(0)
	v_mfma_f32_32x32x16_bf16 v[114:129], v[162:165], v[228:231], v[114:129]
	ds_read_b128 v[166:169], v136 offset:0
	ds_read_b128 v[232:235], v137 offset:0
	s_add_i32 s6, s6, 1
	v_mfma_f32_32x32x16_bf16 v[98:113], v[162:165], v[236:239], v[98:113]
	ds_read_b128 v[240:243], v137 offset:2048
	ds_read_b128 v[208:211], v136 offset:2048
	v_mfma_f32_32x32x16_bf16 v[82:97], v[204:207], v[228:231], v[82:97]
	ds_read_b128 v[216:219], v136 offset:4096
	ds_read_b128 v[224:227], v136 offset:6144
	v_mfma_f32_32x32x16_bf16 v[66:81], v[204:207], v[236:239], v[66:81]
	v_mfma_f32_32x32x16_bf16 v[50:65], v[212:215], v[228:231], v[50:65]
	v_mfma_f32_32x32x16_bf16 v[34:49], v[212:215], v[236:239], v[34:49]
	v_mfma_f32_32x32x16_bf16 v[18:33], v[220:223], v[228:231], v[18:33]
	v_mfma_f32_32x32x16_bf16 v[2:17], v[220:223], v[236:239], v[2:17]
	s_waitcnt vmcnt(0) lgkmcnt(0)
	s_barrier
	s_mov_b32 s7, s73
	s_add_u32 s73, s7, 0x6000
	s_cmp_lt_u32 s73, 0x12000
	s_cselect_b32 s73, s73, 0
	v_mfma_f32_32x32x16_bf16 v[114:129], v[166:169], v[232:235], v[114:129]
	ds_read_b128 v[162:165], v138 offset:0
	ds_read_b128 v[228:231], v139 offset:0
	v_mfma_f32_32x32x16_bf16 v[98:113], v[166:169], v[240:243], v[98:113]
	ds_read_b128 v[236:239], v139 offset:2048
	ds_read_b128 v[204:207], v138 offset:2048
	v_add_u32_e32 v136, s7, v134
	v_add_u32_e32 v137, s7, v135
	v_mfma_f32_32x32x16_bf16 v[82:97], v[208:211], v[232:235], v[82:97]
	ds_read_b128 v[212:215], v138 offset:4096
	ds_read_b128 v[220:223], v138 offset:6144
	v_mfma_f32_32x32x16_bf16 v[66:81], v[208:211], v[240:243], v[66:81]
	v_add_u32_e32 v138, s73, v132
	v_add_u32_e32 v139, s73, v133
	v_mfma_f32_32x32x16_bf16 v[50:65], v[216:219], v[232:235], v[50:65]
	v_mfma_f32_32x32x16_bf16 v[34:49], v[216:219], v[240:243], v[34:49]
	v_mfma_f32_32x32x16_bf16 v[18:33], v[224:227], v[232:235], v[18:33]
	v_mfma_f32_32x32x16_bf16 v[2:17], v[224:227], v[240:243], v[2:17]
	s_waitcnt lgkmcnt(0)
	v_mfma_f32_32x32x16_bf16 v[114:129], v[162:165], v[228:231], v[114:129]
	ds_read_b128 v[166:169], v136 offset:0
	ds_read_b128 v[232:235], v137 offset:0
	s_add_i32 s6, s6, 1
	v_mfma_f32_32x32x16_bf16 v[98:113], v[162:165], v[236:239], v[98:113]
	ds_read_b128 v[240:243], v137 offset:2048
	ds_read_b128 v[208:211], v136 offset:2048
	v_mfma_f32_32x32x16_bf16 v[82:97], v[204:207], v[228:231], v[82:97]
	ds_read_b128 v[216:219], v136 offset:4096
	ds_read_b128 v[224:227], v136 offset:6144
	v_mfma_f32_32x32x16_bf16 v[66:81], v[204:207], v[236:239], v[66:81]
	v_mfma_f32_32x32x16_bf16 v[50:65], v[212:215], v[228:231], v[50:65]
	v_mfma_f32_32x32x16_bf16 v[34:49], v[212:215], v[236:239], v[34:49]
	v_mfma_f32_32x32x16_bf16 v[18:33], v[220:223], v[228:231], v[18:33]
	v_mfma_f32_32x32x16_bf16 v[2:17], v[220:223], v[236:239], v[2:17]
	s_waitcnt lgkmcnt(0)
	v_mfma_f32_32x32x16_bf16 v[114:129], v[166:169], v[232:235], v[114:129]
	v_mfma_f32_32x32x16_bf16 v[98:113], v[166:169], v[240:243], v[98:113]
	v_mfma_f32_32x32x16_bf16 v[82:97], v[208:211], v[232:235], v[82:97]
	v_mfma_f32_32x32x16_bf16 v[66:81], v[208:211], v[240:243], v[66:81]
	v_mfma_f32_32x32x16_bf16 v[50:65], v[216:219], v[232:235], v[50:65]
	v_mfma_f32_32x32x16_bf16 v[34:49], v[216:219], v[240:243], v[34:49]
	v_mfma_f32_32x32x16_bf16 v[18:33], v[224:227], v[232:235], v[18:33]
	v_mfma_f32_32x32x16_bf16 v[2:17], v[224:227], v[240:243], v[2:17]
	s_mov_b32 s14, 31
	s_lshl_b64 s[12:13], s[14:15], 13
	s_movk_i32 s7, 0x7800
	s_movk_i32 s72, 0x6000
	s_mov_b32 s73, 0xc000
	s_movk_i32 s74, 0x104
	s_mov_b32 s75, 0x42ce8ed0
	s_mov_b32 s76, 0xbfb8aa3b
	s_mov_b32 s77, 0x1d730000
	v_mov_b32_e32 v0, v171
	s_barrier
	s_movk_i32 s0, 0x210
	s_waitcnt vmcnt(4)
	v_lshrrev_b32_e32 v130, 1, v0
	v_and_b32_e32 v130, 0xfffffc0, v130
	v_lshrrev_b32_e32 v131, 3, v0
	v_and_or_b32 v130, v131, 4, v130
	v_and_b32_e32 v0, 0x5f, v0
	v_mul_lo_u32 v130, v130, s0
	v_lshl_add_u32 v0, v0, 2, v130
	s_barrier
	ds_write2_b32 v0, v114, v98 offset1:32
	ds_write2_b32 v0, v115, v99 offset0:132 offset1:164
	v_add_u32_e32 v98, 0x400, v0
	ds_write2_b32 v98, v116, v100 offset0:8 offset1:40
	ds_write2_b32 v98, v117, v101 offset0:140 offset1:172
	v_add_u32_e32 v98, 0x1000, v0
	ds_write2_b32 v98, v118, v102 offset0:32 offset1:64
	ds_write2_b32 v98, v119, v103 offset0:164 offset1:196
	v_add_u32_e32 v98, 0x1400, v0
	ds_write2_b32 v98, v120, v104 offset0:40 offset1:72
	ds_write2_b32 v98, v121, v105 offset0:172 offset1:204
	v_add_u32_e32 v98, 0x2000, v0
	ds_write2_b32 v98, v122, v106 offset0:64 offset1:96
	ds_write2_b32 v98, v123, v107 offset0:196 offset1:228
	v_add_u32_e32 v98, 0x2400, v0
	ds_write2_b32 v98, v124, v108 offset0:72 offset1:104
	ds_write2_b32 v98, v125, v109 offset0:204 offset1:236
	v_add_u32_e32 v98, 0x3000, v0
	ds_write2_b32 v98, v126, v110 offset0:96 offset1:128
	v_add_u32_e32 v98, 0x3200, v0
	ds_write2_b32 v98, v127, v111 offset0:100 offset1:132
	v_add_u32_e32 v98, 0x3400, v0
	ds_write2_b32 v98, v128, v112 offset0:104 offset1:136
	v_add_u32_e32 v98, 0x3600, v0
	ds_write2_b32 v98, v129, v113 offset0:108 offset1:140
	v_add_u32_e32 v98, 0x4000, v0
	ds_write2_b32 v98, v82, v66 offset0:128 offset1:160
	v_add_u32_e32 v66, 0x4400, v0
	ds_write2_b32 v66, v83, v67 offset0:4 offset1:36
	ds_write2_b32 v66, v84, v68 offset0:136 offset1:168
	v_add_u32_e32 v66, 0x4800, v0
	ds_write2_b32 v66, v85, v69 offset0:12 offset1:44
	v_add_u32_e32 v66, 0x5000, v0
	ds_write2_b32 v66, v86, v70 offset0:160 offset1:192
	v_add_u32_e32 v66, 0x5400, v0
	ds_write2_b32 v66, v87, v71 offset0:36 offset1:68
	ds_write2_b32 v66, v88, v72 offset0:168 offset1:200
	v_add_u32_e32 v66, 0x5800, v0
	ds_write2_b32 v66, v89, v73 offset0:44 offset1:76
	v_add_u32_e32 v66, 0x6000, v0
	ds_write2_b32 v66, v90, v74 offset0:192 offset1:224
	v_add_u32_e32 v66, 0x6400, v0
	ds_write2_b32 v66, v91, v75 offset0:68 offset1:100
	ds_write2_b32 v66, v92, v76 offset0:200 offset1:232
	v_add_u32_e32 v66, 0x6800, v0
	ds_write2_b32 v66, v93, v77 offset0:76 offset1:108
	v_add_u32_e32 v66, 0x7200, v0
	ds_write2_b32 v66, v94, v78 offset0:96 offset1:128
	v_add_u32_e32 v66, 0x7400, v0
	s_lshr_b32 s14, s42, 2
	ds_write2_b32 v66, v95, v79 offset0:100 offset1:132
	v_add_u32_e32 v66, 0x7600, v0
	v_add_u32_e32 v0, 0x7800, v0
	v_mov_b32_e32 v105, v171
	s_cmp_lt_i32 s14, 14
	s_mov_b64 s[6:7], -1
	ds_write2_b32 v66, v96, v80 offset0:104 offset1:136
	ds_write2_b32 v0, v97, v81 offset0:108 offset1:140
	s_waitcnt lgkmcnt(0)
	s_barrier
	s_cbranch_scc1 .LBB0_439
	s_cmp_gt_i32 s14, 14
	s_cbranch_scc0 .LBB0_436
	s_mov_b64 s[6:7], 0

.LBB0_587:
	s_lshr_b32 s6, s8, 3
	s_and_b32 s9, s8, 56
	v_readlane_b32 s0, v252, 42
	s_and_b32 s6, s6, 0xffffff8
	s_and_b32 s7, s8, 7
	s_or_b32 s10, s9, s0
	v_mov_b32_e32 v6, v171
	s_or_b32 s6, s6, s7
	s_lshl_b32 s7, s10, 21
	v_readlane_b32 s0, v252, 46
	v_lshlrev_b32_e32 v2, 3, v6
	v_readlane_b32 s1, v252, 47
	s_add_u32 s12, s0, s7
	v_ashrrev_i32_e32 v3, 31, v2
	s_addc_u32 s13, s1, 0
	v_lshlrev_b64 v[4:5], 1, v[2:3]
	s_mov_b32 s7, s15
	v_lshl_add_u64 v[154:155], s[12:13], 0, v[4:5]
	s_mov_b64 s[74:75], s[12:13]
	s_lshl_b64 s[12:13], s[6:7], 20
	v_readlane_b32 s0, v252, 34
	v_readlane_b32 s1, v252, 35
	s_add_u32 s12, s0, s12
	s_addc_u32 s13, s1, s13
	v_lshrrev_b32_e32 v3, 2, v6
	v_and_b32_e32 v0, 24, v2
	v_lshl_add_u64 v[156:157], s[12:13], 0, v[4:5]
	s_mov_b64 s[76:77], s[12:13]
	v_mad_u64_u32 v[158:159], s[12:13], v3, 40, v[0:1]
	s_movk_i32 s0, 0x50
	v_and_b32_e32 v2, 0x30, v6
	v_xor_b32_e32 v140, v4, v2
	v_xor_b32_e32 v154, v154, v2
	v_xor_b32_e32 v156, v156, v2
	v_and_b32_e32 v130, 31, v6
	v_lshlrev_b32_e32 v130, 6, v130
	v_lshrrev_b32_e32 v131, 2, v6
	v_and_b32_e32 v131, 3, v131
	v_bfe_u32 v133, v6, 5, 1
	v_xor_b32_e32 v131, v131, v133
	v_lshl_or_b32 v130, v131, 4, v130
	v_lshrrev_b32_e32 v131, 7, v6
	v_lshl_or_b32 v132, v131, 13, v130
	v_bfe_u32 v131, v6, 6, 1
	v_lshl_or_b32 v133, v131, 12, v130
	v_or_b32_e32 v133, 0x4000, v133
	v_xor_b32_e32 v134, 32, v132
	v_xor_b32_e32 v135, 32, v133
	v_lshrrev_b32_e32 v131, 6, v6
	s_nop 1
	v_readfirstlane_b32 s72, v131
	s_nop 3
	s_lshl_b32 s72, s72, 10
	s_waitcnt lgkmcnt(0)
	s_barrier
	s_mov_b32 s14, 0
	s_lshl_b64 s[12:13], s[14:15], 14
	s_add_u32 s12, s12, s74
	s_addc_u32 s13, s13, s75
	s_add_u32 m0, s72, 0x0
	s_nop 0
	global_load_lds_dwordx4 v140, s[12:13]
	s_add_u32 m0, m0, 0x1000
	s_add_u32 s12, s12, 0x1000
	s_addc_u32 s13, s13, 0
	global_load_lds_dwordx4 v140, s[12:13]
	s_add_u32 m0, m0, 0x1000
	s_add_u32 s12, s12, 0x1000
	s_addc_u32 s13, s13, 0
	global_load_lds_dwordx4 v140, s[12:13]
	s_add_u32 m0, m0, 0x1000
	s_add_u32 s12, s12, 0x1000
	s_addc_u32 s13, s13, 0
	global_load_lds_dwordx4 v140, s[12:13]
	s_add_u32 m0, m0, 0x1000
	s_lshl_b64 s[12:13], s[14:15], 13
	s_add_u32 s12, s12, s76
	s_addc_u32 s13, s13, s77
	global_load_lds_dwordx4 v140, s[12:13]
	s_add_u32 m0, m0, 0x1000
	s_add_u32 s12, s12, 0x1000
	s_addc_u32 s13, s13, 0
	global_load_lds_dwordx4 v140, s[12:13]
	s_mov_b32 s14, 1
	s_lshl_b64 s[12:13], s[14:15], 14
	s_add_u32 s12, s12, s74
	s_addc_u32 s13, s13, s75
	s_add_u32 m0, s72, 0x6000
	s_nop 0
	global_load_lds_dwordx4 v140, s[12:13]
	s_add_u32 m0, m0, 0x1000
	s_add_u32 s12, s12, 0x1000
	s_addc_u32 s13, s13, 0
	global_load_lds_dwordx4 v140, s[12:13]
	s_add_u32 m0, m0, 0x1000
	s_add_u32 s12, s12, 0x1000
	s_addc_u32 s13, s13, 0
	global_load_lds_dwordx4 v140, s[12:13]
	s_add_u32 m0, m0, 0x1000
	s_add_u32 s12, s12, 0x1000
	s_addc_u32 s13, s13, 0
	global_load_lds_dwordx4 v140, s[12:13]
	s_add_u32 m0, m0, 0x1000
	s_lshl_b64 s[12:13], s[14:15], 13
	s_add_u32 s12, s12, s76
	s_addc_u32 s13, s13, s77
	global_load_lds_dwordx4 v140, s[12:13]
	s_add_u32 m0, m0, 0x1000
	s_add_u32 s12, s12, 0x1000
	s_addc_u32 s13, s13, 0
	global_load_lds_dwordx4 v140, s[12:13]
	s_mov_b32 s14, 2
	s_lshl_b64 s[12:13], s[14:15], 14
	s_add_u32 s12, s12, s74
	s_addc_u32 s13, s13, s75
	s_add_u32 m0, s72, 0xc000
	s_nop 0
	global_load_lds_dwordx4 v140, s[12:13]
	s_add_u32 m0, m0, 0x1000
	s_add_u32 s12, s12, 0x1000
	s_addc_u32 s13, s13, 0
	global_load_lds_dwordx4 v140, s[12:13]
	s_add_u32 m0, m0, 0x1000
	s_add_u32 s12, s12, 0x1000
	s_addc_u32 s13, s13, 0
	global_load_lds_dwordx4 v140, s[12:13]
	s_add_u32 m0, m0, 0x1000
	s_add_u32 s12, s12, 0x1000
	s_addc_u32 s13, s13, 0
	global_load_lds_dwordx4 v140, s[12:13]
	s_add_u32 m0, m0, 0x1000
	s_lshl_b64 s[12:13], s[14:15], 13
	s_add_u32 s12, s12, s76
	s_addc_u32 s13, s13, s77
	global_load_lds_dwordx4 v140, s[12:13]
	s_add_u32 m0, m0, 0x1000
	s_add_u32 s12, s12, 0x1000
	s_addc_u32 s13, s13, 0
	global_load_lds_dwordx4 v140, s[12:13]
	v_and_b32_e32 v2, 0xfffff9f, v6
	v_mul_lo_u32 v160, v2, s0
	v_or_b32_e32 v2, 0x60, v6
	v_lshrrev_b32_e32 v0, 1, v6
	v_and_b32_e32 v3, 0x5f, v6
	v_mul_lo_u32 v161, v2, s0
	v_mov_b32_e32 v2, 0
	s_mov_b32 s7, 0
	v_and_b32_e32 v0, 16, v0
	v_mul_u32_u24_e32 v159, 0x50, v3
	v_mov_b32_e32 v3, v2
	v_mov_b32_e32 v4, v2
	v_mov_b32_e32 v5, v2
	v_mov_b32_e32 v6, v2
	v_mov_b32_e32 v7, v2
	v_mov_b32_e32 v8, v2
	v_mov_b32_e32 v9, v2
	v_mov_b32_e32 v10, v2
	v_mov_b32_e32 v11, v2
	v_mov_b32_e32 v12, v2
	v_mov_b32_e32 v13, v2
	v_mov_b32_e32 v14, v2
	v_mov_b32_e32 v15, v2
	v_mov_b32_e32 v16, v2
	v_mov_b32_e32 v17, v2
	v_mov_b32_e32 v18, v2
	v_mov_b32_e32 v19, v2
	v_mov_b32_e32 v20, v2
	v_mov_b32_e32 v21, v2
	v_mov_b32_e32 v22, v2
	v_mov_b32_e32 v23, v2
	v_mov_b32_e32 v24, v2
	v_mov_b32_e32 v25, v2
	v_mov_b32_e32 v26, v2
	v_mov_b32_e32 v27, v2
	v_mov_b32_e32 v28, v2
	v_mov_b32_e32 v29, v2
	v_mov_b32_e32 v30, v2
	v_mov_b32_e32 v31, v2
	v_mov_b32_e32 v32, v2
	v_mov_b32_e32 v33, v2
	v_mov_b32_e32 v34, v2
	v_mov_b32_e32 v35, v2
	v_mov_b32_e32 v36, v2
	v_mov_b32_e32 v37, v2
	v_mov_b32_e32 v38, v2
	v_mov_b32_e32 v39, v2
	v_mov_b32_e32 v40, v2
	v_mov_b32_e32 v41, v2
	v_mov_b32_e32 v42, v2
	v_mov_b32_e32 v43, v2
	v_mov_b32_e32 v44, v2
	v_mov_b32_e32 v45, v2
	v_mov_b32_e32 v46, v2
	v_mov_b32_e32 v47, v2
	v_mov_b32_e32 v48, v2
	v_mov_b32_e32 v49, v2
	v_mov_b32_e32 v50, v2
	v_mov_b32_e32 v51, v2
	v_mov_b32_e32 v52, v2
	v_mov_b32_e32 v53, v2
	v_mov_b32_e32 v54, v2
	v_mov_b32_e32 v55, v2
	v_mov_b32_e32 v56, v2
	v_mov_b32_e32 v57, v2
	v_mov_b32_e32 v58, v2
	v_mov_b32_e32 v59, v2
	v_mov_b32_e32 v60, v2
	v_mov_b32_e32 v61, v2
	v_mov_b32_e32 v62, v2
	v_mov_b32_e32 v63, v2
	v_mov_b32_e32 v64, v2
	v_mov_b32_e32 v65, v2
	v_mov_b32_e32 v66, v2
	v_mov_b32_e32 v67, v2
	v_mov_b32_e32 v68, v2
	v_mov_b32_e32 v69, v2
	v_mov_b32_e32 v70, v2
	v_mov_b32_e32 v71, v2
	v_mov_b32_e32 v72, v2
	v_mov_b32_e32 v73, v2
	v_mov_b32_e32 v74, v2
	v_mov_b32_e32 v75, v2
	v_mov_b32_e32 v76, v2
	v_mov_b32_e32 v77, v2
	v_mov_b32_e32 v78, v2
	v_mov_b32_e32 v79, v2
	v_mov_b32_e32 v80, v2
	v_mov_b32_e32 v81, v2
	s_waitcnt vmcnt(17)
	v_mov_b32_e32 v82, v2
	v_mov_b32_e32 v83, v2
	v_mov_b32_e32 v84, v2
	v_mov_b32_e32 v85, v2
	s_waitcnt vmcnt(16)
	v_mov_b32_e32 v86, v2
	v_mov_b32_e32 v87, v2
	v_mov_b32_e32 v88, v2
	v_mov_b32_e32 v89, v2
	s_waitcnt vmcnt(15)
	v_mov_b32_e32 v90, v2
	v_mov_b32_e32 v91, v2
	v_mov_b32_e32 v92, v2
	v_mov_b32_e32 v93, v2
	s_waitcnt vmcnt(14)
	v_mov_b32_e32 v94, v2
	v_mov_b32_e32 v95, v2
	v_mov_b32_e32 v96, v2
	v_mov_b32_e32 v97, v2
	v_mov_b32_e32 v98, v2
	v_mov_b32_e32 v99, v2
	v_mov_b32_e32 v100, v2
	v_mov_b32_e32 v101, v2
	v_mov_b32_e32 v102, v2
	v_mov_b32_e32 v103, v2
	v_mov_b32_e32 v104, v2
	v_mov_b32_e32 v105, v2
	v_mov_b32_e32 v106, v2
	v_mov_b32_e32 v107, v2
	v_mov_b32_e32 v108, v2
	v_mov_b32_e32 v109, v2
	v_mov_b32_e32 v110, v2
	v_mov_b32_e32 v111, v2
	v_mov_b32_e32 v112, v2
	v_mov_b32_e32 v113, v2
	v_mov_b32_e32 v114, v2
	v_mov_b32_e32 v115, v2
	v_mov_b32_e32 v116, v2
	v_mov_b32_e32 v117, v2
	v_mov_b32_e32 v118, v2
	v_mov_b32_e32 v119, v2
	v_mov_b32_e32 v120, v2
	v_mov_b32_e32 v121, v2
	v_mov_b32_e32 v122, v2
	v_mov_b32_e32 v123, v2
	v_mov_b32_e32 v124, v2
	v_mov_b32_e32 v125, v2
	v_mov_b32_e32 v126, v2
	v_mov_b32_e32 v127, v2
	v_mov_b32_e32 v128, v2
	v_mov_b32_e32 v129, v2
	s_waitcnt lgkmcnt(0)
	s_mov_b32 s7, 0
	s_mov_b32 s11, 0
	v_mov_b32_e32 v138, v132
	v_mov_b32_e32 v139, v133
	s_waitcnt vmcnt(12)
	s_barrier
	ds_read_b128 v[162:165], v138 offset:0
	ds_read_b128 v[228:231], v139 offset:0
	ds_read_b128 v[236:239], v139 offset:2048
	ds_read_b128 v[204:207], v138 offset:2048
	ds_read_b128 v[212:215], v138 offset:4096
	ds_read_b128 v[220:223], v138 offset:6144
	s_movk_i32 s73, 0x6000
	v_mov_b32_e32 v136, v134
	v_mov_b32_e32 v137, v135
	v_add_u32_e32 v138, s73, v132
	v_add_u32_e32 v139, s73, v133
.Lg588_loop:
	s_waitcnt lgkmcnt(0)
	v_mfma_f32_32x32x16_bf16 v[114:129], v[162:165], v[228:231], v[114:129]
	ds_read_b128 v[166:169], v136 offset:0
	ds_read_b128 v[232:235], v137 offset:0
	s_add_i32 s7, s7, 1
	s_add_i32 s14, s7, 2
	s_lshl_b64 s[12:13], s[14:15], 14
	s_add_u32 s12, s12, s74
	s_addc_u32 s13, s13, s75
	v_mfma_f32_32x32x16_bf16 v[98:113], v[162:165], v[236:239], v[98:113]
	ds_read_b128 v[240:243], v137 offset:2048
	ds_read_b128 v[208:211], v136 offset:2048
	v_mfma_f32_32x32x16_bf16 v[82:97], v[204:207], v[228:231], v[82:97]
	ds_read_b128 v[216:219], v136 offset:4096
	ds_read_b128 v[224:227], v136 offset:6144
	v_mfma_f32_32x32x16_bf16 v[66:81], v[204:207], v[236:239], v[66:81]
	v_mfma_f32_32x32x16_bf16 v[50:65], v[212:215], v[228:231], v[50:65]
	v_mfma_f32_32x32x16_bf16 v[34:49], v[212:215], v[236:239], v[34:49]
	v_mfma_f32_32x32x16_bf16 v[18:33], v[220:223], v[228:231], v[18:33]
	v_mfma_f32_32x32x16_bf16 v[2:17], v[220:223], v[236:239], v[2:17]
	s_waitcnt vmcnt(6) lgkmcnt(0)
	s_barrier
	s_add_u32 m0, s11, s72
	s_mov_b32 s11, s73
	s_add_u32 s73, s11, 0x6000
	s_cmp_lt_u32 s73, 0x12000
	s_cselect_b32 s73, s73, 0
	v_mfma_f32_32x32x16_bf16 v[114:129], v[166:169], v[232:235], v[114:129]
	ds_read_b128 v[162:165], v138 offset:0
	ds_read_b128 v[228:231], v139 offset:0
	v_mfma_f32_32x32x16_bf16 v[98:113], v[166:169], v[240:243], v[98:113]
	ds_read_b128 v[236:239], v139 offset:2048
	ds_read_b128 v[204:207], v138 offset:2048
	v_add_u32_e32 v136, s11, v134
	v_add_u32_e32 v137, s11, v135
	v_mfma_f32_32x32x16_bf16 v[82:97], v[208:211], v[232:235], v[82:97]
	ds_read_b128 v[212:215], v138 offset:4096
	ds_read_b128 v[220:223], v138 offset:6144
	v_mfma_f32_32x32x16_bf16 v[66:81], v[208:211], v[240:243], v[66:81]
	global_load_lds_dwordx4 v140, s[12:13]
	s_add_u32 m0, m0, 0x1000
	s_add_u32 s12, s12, 0x1000
	s_addc_u32 s13, s13, 0
	v_add_u32_e32 v138, s73, v132
	v_add_u32_e32 v139, s73, v133
	v_mfma_f32_32x32x16_bf16 v[50:65], v[216:219], v[232:235], v[50:65]
	global_load_lds_dwordx4 v140, s[12:13]
	s_add_u32 m0, m0, 0x1000
	s_add_u32 s12, s12, 0x1000
	s_addc_u32 s13, s13, 0
	v_mfma_f32_32x32x16_bf16 v[34:49], v[216:219], v[240:243], v[34:49]
	global_load_lds_dwordx4 v140, s[12:13]
	s_add_u32 m0, m0, 0x1000
	s_add_u32 s12, s12, 0x1000
	s_addc_u32 s13, s13, 0
	v_mfma_f32_32x32x16_bf16 v[18:33], v[224:227], v[232:235], v[18:33]
	global_load_lds_dwordx4 v140, s[12:13]
	s_add_u32 m0, m0, 0x1000
	s_lshl_b64 s[12:13], s[14:15], 13
	s_add_u32 s12, s12, s76
	s_addc_u32 s13, s13, s77
	v_mfma_f32_32x32x16_bf16 v[2:17], v[224:227], v[240:243], v[2:17]
	global_load_lds_dwordx4 v140, s[12:13]
	s_add_u32 m0, m0, 0x1000
	s_add_u32 s12, s12, 0x1000
	s_addc_u32 s13, s13, 0
	s_nop 0
	global_load_lds_dwordx4 v140, s[12:13]
	s_cmp_lg_u32 s7, 125
	s_cbranch_scc1 .Lg588_loop
	s_waitcnt lgkmcnt(0)
	v_mfma_f32_32x32x16_bf16 v[114:129], v[162:165], v[228:231], v[114:129]
	ds_read_b128 v[166:169], v136 offset:0
	ds_read_b128 v[232:235], v137 offset:0
	s_add_i32 s7, s7, 1
	v_mfma_f32_32x32x16_bf16 v[98:113], v[162:165], v[236:239], v[98:113]
	ds_read_b128 v[240:243], v137 offset:2048
	ds_read_b128 v[208:211], v136 offset:2048
	v_mfma_f32_32x32x16_bf16 v[82:97], v[204:207], v[228:231], v[82:97]
	ds_read_b128 v[216:219], v136 offset:4096
	ds_read_b128 v[224:227], v136 offset:6144
	v_mfma_f32_32x32x16_bf16 v[66:81], v[204:207], v[236:239], v[66:81]
	v_mfma_f32_32x32x16_bf16 v[50:65], v[212:215], v[228:231], v[50:65]
	v_mfma_f32_32x32x16_bf16 v[34:49], v[212:215], v[236:239], v[34:49]
	v_mfma_f32_32x32x16_bf16 v[18:33], v[220:223], v[228:231], v[18:33]
	v_mfma_f32_32x32x16_bf16 v[2:17], v[220:223], v[236:239], v[2:17]
	s_waitcnt vmcnt(6) lgkmcnt(0)
	s_barrier
	s_mov_b32 s11, s73
	s_add_u32 s73, s11, 0x6000
	s_cmp_lt_u32 s73, 0x12000
	s_cselect_b32 s73, s73, 0
	v_mfma_f32_32x32x16_bf16 v[114:129], v[166:169], v[232:235], v[114:129]
	ds_read_b128 v[162:165], v138 offset:0
	ds_read_b128 v[228:231], v139 offset:0
	v_mfma_f32_32x32x16_bf16 v[98:113], v[166:169], v[240:243], v[98:113]
	ds_read_b128 v[236:239], v139 offset:2048
	ds_read_b128 v[204:207], v138 offset:2048
	v_add_u32_e32 v136, s11, v134
	v_add_u32_e32 v137, s11, v135
	v_mfma_f32_32x32x16_bf16 v[82:97], v[208:211], v[232:235], v[82:97]
	ds_read_b128 v[212:215], v138 offset:4096
	ds_read_b128 v[220:223], v138 offset:6144
	v_mfma_f32_32x32x16_bf16 v[66:81], v[208:211], v[240:243], v[66:81]
	v_add_u32_e32 v138, s73, v132
	v_add_u32_e32 v139, s73, v133
	v_mfma_f32_32x32x16_bf16 v[50:65], v[216:219], v[232:235], v[50:65]
	v_mfma_f32_32x32x16_bf16 v[34:49], v[216:219], v[240:243], v[34:49]
	v_mfma_f32_32x32x16_bf16 v[18:33], v[224:227], v[232:235], v[18:33]
	v_mfma_f32_32x32x16_bf16 v[2:17], v[224:227], v[240:243], v[2:17]
	s_waitcnt lgkmcnt(0)
	v_mfma_f32_32x32x16_bf16 v[114:129], v[162:165], v[228:231], v[114:129]
	ds_read_b128 v[166:169], v136 offset:0
	ds_read_b128 v[232:235], v137 offset:0
	s_add_i32 s7, s7, 1
	v_mfma_f32_32x32x16_bf16 v[98:113], v[162:165], v[236:239], v[98:113]
	ds_read_b128 v[240:243], v137 offset:2048
	ds_read_b128 v[208:211], v136 offset:2048
	v_mfma_f32_32x32x16_bf16 v[82:97], v[204:207], v[228:231], v[82:97]
	ds_read_b128 v[216:219], v136 offset:4096
	ds_read_b128 v[224:227], v136 offset:6144
	v_mfma_f32_32x32x16_bf16 v[66:81], v[204:207], v[236:239], v[66:81]
	v_mfma_f32_32x32x16_bf16 v[50:65], v[212:215], v[228:231], v[50:65]
	v_mfma_f32_32x32x16_bf16 v[34:49], v[212:215], v[236:239], v[34:49]
	v_mfma_f32_32x32x16_bf16 v[18:33], v[220:223], v[228:231], v[18:33]
	v_mfma_f32_32x32x16_bf16 v[2:17], v[220:223], v[236:239], v[2:17]
	s_waitcnt vmcnt(0) lgkmcnt(0)
	s_barrier
	s_mov_b32 s11, s73
	s_add_u32 s73, s11, 0x6000
	s_cmp_lt_u32 s73, 0x12000
	s_cselect_b32 s73, s73, 0
	v_mfma_f32_32x32x16_bf16 v[114:129], v[166:169], v[232:235], v[114:129]
	ds_read_b128 v[162:165], v138 offset:0
	ds_read_b128 v[228:231], v139 offset:0
	v_mfma_f32_32x32x16_bf16 v[98:113], v[166:169], v[240:243], v[98:113]
	ds_read_b128 v[236:239], v139 offset:2048
	ds_read_b128 v[204:207], v138 offset:2048
	v_add_u32_e32 v136, s11, v134
	v_add_u32_e32 v137, s11, v135
	v_mfma_f32_32x32x16_bf16 v[82:97], v[208:211], v[232:235], v[82:97]
	ds_read_b128 v[212:215], v138 offset:4096
	ds_read_b128 v[220:223], v138 offset:6144
	v_mfma_f32_32x32x16_bf16 v[66:81], v[208:211], v[240:243], v[66:81]
	v_add_u32_e32 v138, s73, v132
	v_add_u32_e32 v139, s73, v133
	v_mfma_f32_32x32x16_bf16 v[50:65], v[216:219], v[232:235], v[50:65]
	v_mfma_f32_32x32x16_bf16 v[34:49], v[216:219], v[240:243], v[34:49]
	v_mfma_f32_32x32x16_bf16 v[18:33], v[224:227], v[232:235], v[18:33]
	v_mfma_f32_32x32x16_bf16 v[2:17], v[224:227], v[240:243], v[2:17]
	s_waitcnt lgkmcnt(0)
	v_mfma_f32_32x32x16_bf16 v[114:129], v[162:165], v[228:231], v[114:129]
	ds_read_b128 v[166:169], v136 offset:0
	ds_read_b128 v[232:235], v137 offset:0
	s_add_i32 s7, s7, 1
	v_mfma_f32_32x32x16_bf16 v[98:113], v[162:165], v[236:239], v[98:113]
	ds_read_b128 v[240:243], v137 offset:2048
	ds_read_b128 v[208:211], v136 offset:2048
	v_mfma_f32_32x32x16_bf16 v[82:97], v[204:207], v[228:231], v[82:97]
	ds_read_b128 v[216:219], v136 offset:4096
	ds_read_b128 v[224:227], v136 offset:6144
	v_mfma_f32_32x32x16_bf16 v[66:81], v[204:207], v[236:239], v[66:81]
	v_mfma_f32_32x32x16_bf16 v[50:65], v[212:215], v[228:231], v[50:65]
	v_mfma_f32_32x32x16_bf16 v[34:49], v[212:215], v[236:239], v[34:49]
	v_mfma_f32_32x32x16_bf16 v[18:33], v[220:223], v[228:231], v[18:33]
	v_mfma_f32_32x32x16_bf16 v[2:17], v[220:223], v[236:239], v[2:17]
	s_waitcnt lgkmcnt(0)
	v_mfma_f32_32x32x16_bf16 v[114:129], v[166:169], v[232:235], v[114:129]
	v_mfma_f32_32x32x16_bf16 v[98:113], v[166:169], v[240:243], v[98:113]
	v_mfma_f32_32x32x16_bf16 v[82:97], v[208:211], v[232:235], v[82:97]
	v_mfma_f32_32x32x16_bf16 v[66:81], v[208:211], v[240:243], v[66:81]
	v_mfma_f32_32x32x16_bf16 v[50:65], v[216:219], v[232:235], v[50:65]
	v_mfma_f32_32x32x16_bf16 v[34:49], v[216:219], v[240:243], v[34:49]
	v_mfma_f32_32x32x16_bf16 v[18:33], v[224:227], v[232:235], v[18:33]
	v_mfma_f32_32x32x16_bf16 v[2:17], v[224:227], v[240:243], v[2:17]
	s_mov_b32 s14, 127
	s_lshl_b64 s[12:13], s[14:15], 13
	s_movk_i32 s11, 0x7800
	s_movk_i32 s72, 0x6000
	s_mov_b32 s73, 0xc000
	s_movk_i32 s74, 0x104
	s_mov_b32 s75, 0x42ce8ed0
	s_mov_b32 s76, 0xbfb8aa3b
	s_mov_b32 s77, 0x1d730000
	v_mov_b32_e32 v0, v171
	s_barrier
	s_movk_i32 s0, 0x210
	s_waitcnt vmcnt(4)
	v_lshrrev_b32_e32 v130, 1, v0
	v_and_b32_e32 v130, 0xfffffc0, v130
	v_lshrrev_b32_e32 v131, 3, v0
	v_and_or_b32 v130, v131, 4, v130
	v_and_b32_e32 v0, 0x5f, v0
	v_mul_lo_u32 v130, v130, s0
	v_lshl_add_u32 v0, v0, 2, v130
	s_barrier
	ds_write2_b32 v0, v114, v98 offset1:32
	ds_write2_b32 v0, v115, v99 offset0:132 offset1:164
	v_add_u32_e32 v98, 0x400, v0
	ds_write2_b32 v98, v116, v100 offset0:8 offset1:40
	ds_write2_b32 v98, v117, v101 offset0:140 offset1:172
	v_add_u32_e32 v98, 0x1000, v0
	ds_write2_b32 v98, v118, v102 offset0:32 offset1:64
	ds_write2_b32 v98, v119, v103 offset0:164 offset1:196
	v_add_u32_e32 v98, 0x1400, v0
	ds_write2_b32 v98, v120, v104 offset0:40 offset1:72
	ds_write2_b32 v98, v121, v105 offset0:172 offset1:204
	v_add_u32_e32 v98, 0x2000, v0
	ds_write2_b32 v98, v122, v106 offset0:64 offset1:96
	ds_write2_b32 v98, v123, v107 offset0:196 offset1:228
	v_add_u32_e32 v98, 0x2400, v0
	ds_write2_b32 v98, v124, v108 offset0:72 offset1:104
	ds_write2_b32 v98, v125, v109 offset0:204 offset1:236
	v_add_u32_e32 v98, 0x3000, v0
	ds_write2_b32 v98, v126, v110 offset0:96 offset1:128
	v_add_u32_e32 v98, 0x3200, v0
	ds_write2_b32 v98, v127, v111 offset0:100 offset1:132
	v_add_u32_e32 v98, 0x3400, v0
	ds_write2_b32 v98, v128, v112 offset0:104 offset1:136
	v_add_u32_e32 v98, 0x3600, v0
	ds_write2_b32 v98, v129, v113 offset0:108 offset1:140
	v_add_u32_e32 v98, 0x4000, v0
	ds_write2_b32 v98, v82, v66 offset0:128 offset1:160
	v_add_u32_e32 v66, 0x4400, v0
	ds_write2_b32 v66, v83, v67 offset0:4 offset1:36
	ds_write2_b32 v66, v84, v68 offset0:136 offset1:168
	v_add_u32_e32 v66, 0x4800, v0
	ds_write2_b32 v66, v85, v69 offset0:12 offset1:44
	v_add_u32_e32 v66, 0x5000, v0
	s_lshl_b32 s10, s10, 8
	ds_write2_b32 v66, v86, v70 offset0:160 offset1:192
	v_add_u32_e32 v66, 0x5400, v0
	s_lshl_b32 s11, s6, 7
	ds_write2_b32 v66, v87, v71 offset0:36 offset1:68
	ds_write2_b32 v66, v88, v72 offset0:168 offset1:200
	v_add_u32_e32 v66, 0x5800, v0
	s_add_i32 s6, s10, 0xffffe000
	ds_write2_b32 v66, v89, v73 offset0:44 offset1:76
	v_add_u32_e32 v66, 0x6000, v0
	s_lshr_b32 s6, s6, 12
	ds_write2_b32 v66, v90, v74 offset0:192 offset1:224
	v_add_u32_e32 v66, 0x6400, v0
	s_mulk_i32 s6, 0x1800
	ds_write2_b32 v66, v91, v75 offset0:68 offset1:100
	ds_write2_b32 v66, v92, v76 offset0:200 offset1:232
	v_add_u32_e32 v66, 0x6800, v0
	s_addk_i32 s6, 0x1800
	ds_write2_b32 v66, v93, v77 offset0:76 offset1:108
	v_add_u32_e32 v66, 0x7200, v0
	s_cmp_gt_u32 s9, 31
	ds_write2_b32 v66, v94, v78 offset0:96 offset1:128
	v_add_u32_e32 v66, 0x7400, v0
	s_cselect_b32 s14, s6, 0
	ds_write2_b32 v66, v95, v79 offset0:100 offset1:132
	v_add_u32_e32 v66, 0x7600, v0
	v_add_u32_e32 v0, 0x7800, v0
	v_mov_b32_e32 v84, v171
	s_lshl_b64 s[6:7], s[14:15], 2
	ds_write2_b32 v66, v96, v80 offset0:104 offset1:136
	ds_write2_b32 v0, v97, v81 offset0:108 offset1:140
	s_waitcnt lgkmcnt(0)
	s_barrier
	s_add_u32 s6, s61, s6
	v_lshlrev_b32_e32 v0, 3, v84
	v_and_b32_e32 v0, 0x78, v0
	s_addc_u32 s7, s53, s7
	v_or_b32_e32 v0, s11, v0
	s_add_u32 s6, s6, 0x1d645000
	s_addc_u32 s7, s7, 0
	v_lshlrev_b64 v[82:83], 2, v[0:1]
	v_lshl_add_u64 v[70:71], s[6:7], 0, v[82:83]
	v_lshl_add_u64 v[78:79], s[4:5], 0, v[82:83]
	global_load_dwordx4 v[66:69], v[70:71], off offset:16
	s_nop 0
	global_load_dwordx4 v[70:73], v[70:71], off
	s_nop 0
	global_load_dwordx4 v[74:77], v[78:79], off offset:16
	s_nop 0
	global_load_dwordx4 v[78:81], v[78:79], off
	v_ashrrev_i32_e32 v0, 4, v84
	v_mul_lo_u32 v85, v0, s0
	v_and_b32_e32 v84, 15, v84
	s_mov_b32 s9, 0
	v_lshl_add_u64 v[82:83], s[56:57], 0, v[82:83]
	v_lshl_add_u32 v84, v84, 5, v85
	v_lshlrev_b32_e32 v85, 1, v0
